# u9 with three priority levels: MFMA stretch 2, staging part 1, tile epilogue and prologue code 0
# baseline (speedup 1.0000x reference)
; DI void gemm_128_deep(const bf16_t* __restrict__ A, int lda, const bf16_t* __restrict__ B, int ldb, int K, f32x16 (&acc)[2][2], bf16_t* sA, bf16_t* sBunused) {
;     ...
;   for (int k0 = 0; k0 < K - 256; k0 += 128) {
;     MMA_TILE(0)
;     ST_LDS(1, qa0, qa1, qa2, qa3, qb0, qb1, qb2, qb3)
;     GL_Q(k0 + 192)
;     __syncthreads();
;     MMA_TILE(1)
;     ST_LDS(0, pa0, pa1, pa2, pa3, pb0, pb1, pb2, pb3)
;     GL_P(k0 + 256)
;     __syncthreads();
;   }
.LBB0_208:
	ds_read_b128 v[168:171], v128
	ds_read_b128 v[172:175], v129 offset:18432
	ds_read_b128 v[176:179], v128 offset:32
	ds_read_b128 v[180:183], v129 offset:18464
	ds_read_b128 v[184:187], v129 offset:23040
	ds_read_b128 v[188:191], v129 offset:23072
	s_mov_b32 s45, 0x1304000
	s_waitcnt lgkmcnt(4)
	v_mfma_f32_32x32x16_bf16 v[48:63], v[168:171], v[172:175], v[48:63]
	s_mov_b32 s46, 0x1324000
	s_mov_b32 s47, 0x1344000
	s_mov_b32 s48, 0x1364000
	s_addk_i32 s43, 0x80
	s_cmpk_lt_u32 s43, 0x680
	s_waitcnt lgkmcnt(1)
	v_mfma_f32_32x32x16_bf16 v[32:47], v[168:171], v[184:187], v[32:47]
	ds_read_b128 v[168:171], v128 offset:4608
	ds_read_b128 v[192:195], v128 offset:4640
	s_waitcnt lgkmcnt(1)
	v_mfma_f32_32x32x16_bf16 v[16:31], v[168:171], v[172:175], v[16:31]
	v_mfma_f32_32x32x16_bf16 v[0:15], v[168:171], v[184:187], v[0:15]
	v_mfma_f32_32x32x16_bf16 v[48:63], v[176:179], v[180:183], v[48:63]
	v_mfma_f32_32x32x16_bf16 v[32:47], v[176:179], v[188:191], v[32:47]
	s_waitcnt lgkmcnt(0)
	v_mfma_f32_32x32x16_bf16 v[16:31], v[192:195], v[180:183], v[16:31]
	ds_read_b128 v[168:171], v129 offset:18496
	ds_read_b128 v[172:175], v128 offset:64
	ds_read_b128 v[176:179], v128 offset:96
	ds_read_b128 v[180:183], v128 offset:4672
	ds_read_b128 v[184:187], v128 offset:4704
	v_mfma_f32_32x32x16_bf16 v[0:15], v[192:195], v[188:191], v[0:15]
	ds_read_b128 v[188:191], v129 offset:18528
	ds_read_b128 v[192:195], v129 offset:23104
	ds_read_b128 v[196:199], v129 offset:23136
	s_setprio 1
	s_waitcnt vmcnt(15)
	ds_write_b128 v130, v[96:99] offset:36864
	s_waitcnt vmcnt(14)
	ds_write_b128 v130, v[100:103] offset:41472
	s_waitcnt vmcnt(13)
	ds_write_b128 v130, v[104:107] offset:46080
	s_waitcnt vmcnt(12)
	ds_write_b128 v130, v[108:111] offset:50688
	v_lshl_add_u64 v[96:97], v[150:151], 0, v[156:157]
	v_add_co_u32_e32 v152, vcc, s83, v96
	v_lshl_add_u64 v[98:99], v[148:149], 0, v[156:157]
	s_nop 0
	v_addc_co_u32_e32 v153, vcc, 0, v97, vcc
	v_add_co_u32_e32 v200, vcc, s84, v96
	s_waitcnt lgkmcnt(10)
	v_mfma_f32_32x32x16_bf16 v[48:63], v[172:175], v[168:171], v[48:63]
	v_addc_co_u32_e32 v201, vcc, 0, v97, vcc
	v_add_co_u32_e32 v202, vcc, s85, v96
	s_waitcnt vmcnt(11)
	ds_write_b128 v130, v[112:115] offset:55296
	s_waitcnt vmcnt(10)
	ds_write_b128 v130, v[116:119] offset:59904
	s_waitcnt vmcnt(9)
	ds_write_b128 v130, v[120:123] offset:64512
	s_waitcnt vmcnt(8)
	ds_write_b128 v131, v[124:127] offset:13824
	v_addc_co_u32_e32 v203, vcc, 0, v97, vcc
	s_waitcnt lgkmcnt(9)
	v_mfma_f32_32x32x16_bf16 v[32:47], v[172:175], v[192:195], v[32:47]
	v_add_co_u32_e32 v204, vcc, s86, v96
	v_lshl_add_u64 v[148:149], v[148:149], 0, s[94:95]
	s_nop 0
	v_addc_co_u32_e32 v205, vcc, 0, v97, vcc
	v_add_co_u32_e32 v206, vcc, s45, v98
	v_mfma_f32_32x32x16_bf16 v[16:31], v[180:183], v[168:171], v[16:31]
	s_nop 0
	v_addc_co_u32_e32 v207, vcc, 0, v99, vcc
	v_add_co_u32_e32 v208, vcc, s46, v98
	v_lshl_add_u64 v[150:151], v[150:151], 0, s[94:95]
	s_nop 0
	v_addc_co_u32_e32 v209, vcc, 0, v99, vcc
	v_mfma_f32_32x32x16_bf16 v[0:15], v[180:183], v[192:195], v[0:15]
	v_add_co_u32_e32 v210, vcc, s47, v98
	s_nop 1
	v_addc_co_u32_e32 v211, vcc, 0, v99, vcc
	v_add_co_u32_e32 v212, vcc, s48, v98
	v_mfma_f32_32x32x16_bf16 v[48:63], v[176:179], v[188:191], v[48:63]
	s_nop 0
	v_addc_co_u32_e32 v213, vcc, 0, v99, vcc
	global_load_dwordx4 v[96:99], v[152:153], off offset:2176
	global_load_dwordx4 v[100:103], v[200:201], off offset:2176
	global_load_dwordx4 v[104:107], v[202:203], off offset:2176
	global_load_dwordx4 v[108:111], v[204:205], off offset:2176
	global_load_dwordx4 v[112:115], v[206:207], off offset:2176
	global_load_dwordx4 v[116:119], v[208:209], off offset:2176
	global_load_dwordx4 v[120:123], v[210:211], off offset:2176
	global_load_dwordx4 v[124:127], v[212:213], off offset:2176
	s_waitcnt lgkmcnt(0)
	s_barrier
	s_setprio 2
	v_mfma_f32_32x32x16_bf16 v[32:47], v[176:179], v[196:199], v[32:47]
	ds_read_b128 v[168:171], v128 offset:36864
	ds_read_b128 v[172:175], v129 offset:55296
	ds_read_b128 v[176:179], v128 offset:36896
	ds_read_b128 v[180:183], v129 offset:55328
	v_mfma_f32_32x32x16_bf16 v[16:31], v[184:187], v[188:191], v[16:31]
	v_mfma_f32_32x32x16_bf16 v[0:15], v[184:187], v[196:199], v[0:15]
	ds_read_b128 v[184:187], v129 offset:59904
	ds_read_b128 v[188:191], v129 offset:59936
	s_waitcnt lgkmcnt(4)
	v_mfma_f32_32x32x16_bf16 v[48:63], v[168:171], v[172:175], v[48:63]
	s_waitcnt lgkmcnt(1)
	v_mfma_f32_32x32x16_bf16 v[32:47], v[168:171], v[184:187], v[32:47]
	ds_read_b128 v[168:171], v128 offset:41472
	ds_read_b128 v[192:195], v128 offset:41504
	s_waitcnt lgkmcnt(1)
	v_mfma_f32_32x32x16_bf16 v[16:31], v[168:171], v[172:175], v[16:31]
	v_mfma_f32_32x32x16_bf16 v[0:15], v[168:171], v[184:187], v[0:15]
	v_mfma_f32_32x32x16_bf16 v[48:63], v[176:179], v[180:183], v[48:63]
	v_mfma_f32_32x32x16_bf16 v[32:47], v[176:179], v[188:191], v[32:47]
	s_waitcnt lgkmcnt(0)
	v_mfma_f32_32x32x16_bf16 v[16:31], v[192:195], v[180:183], v[16:31]
	ds_read_b128 v[168:171], v128 offset:36928
	ds_read_b128 v[172:175], v129 offset:55360
	ds_read_b128 v[176:179], v128 offset:36960
	ds_read_b128 v[180:183], v129 offset:55392
	v_mfma_f32_32x32x16_bf16 v[0:15], v[192:195], v[188:191], v[0:15]
	ds_read_b128 v[184:187], v129 offset:59968
	ds_read_b128 v[188:191], v129 offset:60000
	s_waitcnt lgkmcnt(4)
	v_mfma_f32_32x32x16_bf16 v[48:63], v[168:171], v[172:175], v[48:63]
	s_waitcnt lgkmcnt(1)
	v_mfma_f32_32x32x16_bf16 v[32:47], v[168:171], v[184:187], v[32:47]
	ds_read_b128 v[168:171], v128 offset:41536
	ds_read_b128 v[192:195], v128 offset:41568
	s_setprio 1
	s_waitcnt vmcnt(13)
	ds_write_b128 v130, v[92:95]
	ds_write_b128 v130, v[64:67] offset:4608
	ds_write_b128 v130, v[68:71] offset:9216
	s_waitcnt vmcnt(11)
	ds_write_b128 v130, v[84:87] offset:13824
	ds_write_b128 v130, v[72:75] offset:18432
	s_waitcnt vmcnt(10)
	ds_write_b128 v130, v[76:79] offset:23040
	s_waitcnt vmcnt(9)
	ds_write_b128 v130, v[80:83] offset:27648
	s_waitcnt vmcnt(8)
	ds_write_b128 v130, v[88:91] offset:32256
	global_load_dwordx4 v[92:95], v[152:153], off offset:2304
	global_load_dwordx4 v[64:67], v[200:201], off offset:2304
	global_load_dwordx4 v[68:71], v[202:203], off offset:2304
	global_load_dwordx4 v[84:87], v[204:205], off offset:2304
	global_load_dwordx4 v[72:75], v[206:207], off offset:2304
	global_load_dwordx4 v[76:79], v[208:209], off offset:2304
	global_load_dwordx4 v[80:83], v[210:211], off offset:2304
	global_load_dwordx4 v[88:91], v[212:213], off offset:2304
	s_waitcnt lgkmcnt(0)
	s_barrier
; DI void gemm_128_deep(const bf16_t* __restrict__ A, int lda, const bf16_t* __restrict__ B, int ldb, int K, f32x16 (&acc)[2][2], bf16_t* sA, bf16_t* sBunused) {
;     ...
;   for (int k0 = 0; k0 < K - 256; k0 += 128) {
;     MMA_TILE(0)
;     ST_LDS(1, qa0, qa1, qa2, qa3, qb0, qb1, qb2, qb3)
;     GL_Q(k0 + 192)
;     __syncthreads();
;     MMA_TILE(1)
;     ST_LDS(0, pa0, pa1, pa2, pa3, pb0, pb1, pb2, pb3)
;     GL_P(k0 + 256)
;     __syncthreads();
;   }
;   MMA_TILE(0)
;   ST_LDS(1, qa0, qa1, qa2, qa3, qb0, qb1, qb2, qb3)
;   GL_Q(K - 64)
;   __syncthreads();
;   MMA_TILE(1)
;   ST_LDS(0, pa0, pa1, pa2, pa3, pb0, pb1, pb2, pb3)
;   __syncthreads();
	s_setprio 2
	v_mfma_f32_32x32x16_bf16 v[16:31], v[168:171], v[172:175], v[16:31]
	v_mfma_f32_32x32x16_bf16 v[0:15], v[168:171], v[184:187], v[0:15]
	v_mfma_f32_32x32x16_bf16 v[48:63], v[176:179], v[180:183], v[48:63]
	v_mfma_f32_32x32x16_bf16 v[32:47], v[176:179], v[188:191], v[32:47]
	v_mfma_f32_32x32x16_bf16 v[16:31], v[192:195], v[180:183], v[16:31]
	v_mfma_f32_32x32x16_bf16 v[0:15], v[192:195], v[188:191], v[0:15]
	s_cbranch_scc1 .LBB0_208
	ds_read_b128 v[148:151], v128
	ds_read_b128 v[168:171], v129 offset:18432
	ds_read_b128 v[172:175], v129 offset:23040
	s_mov_b64 s[52:53], -1
	s_cmp_gt_i32 s60, 15
	s_waitcnt lgkmcnt(1)
	v_mfma_f32_32x32x16_bf16 v[48:63], v[148:151], v[168:171], v[48:63]
	s_waitcnt lgkmcnt(0)
	v_mfma_f32_32x32x16_bf16 v[32:47], v[148:151], v[172:175], v[32:47]
	ds_read_b128 v[148:151], v128 offset:4608
	s_waitcnt lgkmcnt(0)
	v_mfma_f32_32x32x16_bf16 v[16:31], v[148:151], v[168:171], v[16:31]
	v_mfma_f32_32x32x16_bf16 v[0:15], v[148:151], v[172:175], v[0:15]
	ds_read_b128 v[148:151], v128 offset:32
	ds_read_b128 v[168:171], v129 offset:18464
	ds_read_b128 v[172:175], v129 offset:23072
	s_waitcnt lgkmcnt(1)
	v_mfma_f32_32x32x16_bf16 v[48:63], v[148:151], v[168:171], v[48:63]
	s_waitcnt lgkmcnt(0)
	v_mfma_f32_32x32x16_bf16 v[32:47], v[148:151], v[172:175], v[32:47]
	ds_read_b128 v[148:151], v128 offset:4640
	s_waitcnt lgkmcnt(0)
	v_mfma_f32_32x32x16_bf16 v[16:31], v[148:151], v[168:171], v[16:31]
	v_mfma_f32_32x32x16_bf16 v[0:15], v[148:151], v[172:175], v[0:15]
	ds_read_b128 v[148:151], v128 offset:64
	ds_read_b128 v[168:171], v129 offset:18496
	ds_read_b128 v[172:175], v129 offset:23104
	s_waitcnt lgkmcnt(1)
	v_mfma_f32_32x32x16_bf16 v[48:63], v[148:151], v[168:171], v[48:63]
	s_waitcnt lgkmcnt(0)
	v_mfma_f32_32x32x16_bf16 v[32:47], v[148:151], v[172:175], v[32:47]
	ds_read_b128 v[148:151], v128 offset:4672
	s_waitcnt lgkmcnt(0)
	v_mfma_f32_32x32x16_bf16 v[16:31], v[148:151], v[168:171], v[16:31]
	v_mfma_f32_32x32x16_bf16 v[0:15], v[148:151], v[172:175], v[0:15]
	ds_read_b128 v[148:151], v128 offset:96
	ds_read_b128 v[168:171], v129 offset:18528
	ds_read_b128 v[172:175], v129 offset:23136
	s_waitcnt lgkmcnt(1)
	v_mfma_f32_32x32x16_bf16 v[48:63], v[148:151], v[168:171], v[48:63]
	s_waitcnt lgkmcnt(0)
	v_mfma_f32_32x32x16_bf16 v[32:47], v[148:151], v[172:175], v[32:47]
	ds_read_b128 v[148:151], v128 offset:4704
	s_setprio 1
	s_waitcnt vmcnt(15)
	ds_write_b128 v130, v[96:99] offset:36864
	s_waitcnt vmcnt(14)
	ds_write_b128 v130, v[100:103] offset:41472
	s_waitcnt vmcnt(13)
	ds_write_b128 v130, v[104:107] offset:46080
	s_waitcnt vmcnt(12)
	ds_write_b128 v130, v[108:111] offset:50688
	s_waitcnt vmcnt(11)
	ds_write_b128 v130, v[112:115] offset:55296
	s_waitcnt vmcnt(10)
	ds_write_b128 v130, v[116:119] offset:59904
	s_waitcnt vmcnt(9)
	ds_write_b128 v130, v[120:123] offset:64512
	s_waitcnt vmcnt(8)
	ds_write_b128 v131, v[124:127] offset:13824
	global_load_dwordx4 v[96:99], v[142:143], off offset:3968
	global_load_dwordx4 v[100:103], v[138:139], off offset:3968
	global_load_dwordx4 v[104:107], v[144:145], off offset:3968
	global_load_dwordx4 v[108:111], v[146:147], off offset:3968
	global_load_dwordx4 v[112:115], v[132:133], off offset:3968
	global_load_dwordx4 v[116:119], v[134:135], off offset:3968
	global_load_dwordx4 v[120:123], v[136:137], off offset:3968
	global_load_dwordx4 v[124:127], v[140:141], off offset:3968
	s_waitcnt lgkmcnt(0)
	s_barrier
	s_setprio 2
	ds_read_b128 v[132:135], v128 offset:36864
	ds_read_b128 v[136:139], v129 offset:55296
	ds_read_b128 v[140:143], v129 offset:59904
	s_waitcnt lgkmcnt(1)
	v_mfma_f32_32x32x16_bf16 v[48:63], v[132:135], v[136:139], v[48:63]
	s_waitcnt lgkmcnt(0)
	v_mfma_f32_32x32x16_bf16 v[32:47], v[132:135], v[140:143], v[32:47]
	ds_read_b128 v[132:135], v128 offset:41472
	v_mfma_f32_32x32x16_bf16 v[16:31], v[148:151], v[168:171], v[16:31]
	v_mfma_f32_32x32x16_bf16 v[0:15], v[148:151], v[172:175], v[0:15]
	s_waitcnt lgkmcnt(0)
	v_mfma_f32_32x32x16_bf16 v[16:31], v[132:135], v[136:139], v[16:31]
	v_mfma_f32_32x32x16_bf16 v[0:15], v[132:135], v[140:143], v[0:15]
	ds_read_b128 v[132:135], v128 offset:36896
	ds_read_b128 v[136:139], v129 offset:55328
	ds_read_b128 v[140:143], v129 offset:59936
	s_waitcnt lgkmcnt(1)
	v_mfma_f32_32x32x16_bf16 v[48:63], v[132:135], v[136:139], v[48:63]
	s_waitcnt lgkmcnt(0)
	v_mfma_f32_32x32x16_bf16 v[32:47], v[132:135], v[140:143], v[32:47]
	ds_read_b128 v[132:135], v128 offset:41504
	s_waitcnt lgkmcnt(0)
	v_mfma_f32_32x32x16_bf16 v[16:31], v[132:135], v[136:139], v[16:31]
	v_mfma_f32_32x32x16_bf16 v[0:15], v[132:135], v[140:143], v[0:15]
	ds_read_b128 v[132:135], v128 offset:36928
	ds_read_b128 v[136:139], v129 offset:55360
	ds_read_b128 v[140:143], v129 offset:59968
	s_waitcnt lgkmcnt(1)
	v_mfma_f32_32x32x16_bf16 v[48:63], v[132:135], v[136:139], v[48:63]
	s_waitcnt lgkmcnt(0)
	v_mfma_f32_32x32x16_bf16 v[32:47], v[132:135], v[140:143], v[32:47]
	ds_read_b128 v[132:135], v128 offset:41536
	s_waitcnt lgkmcnt(0)
	v_mfma_f32_32x32x16_bf16 v[16:31], v[132:135], v[136:139], v[16:31]
	v_mfma_f32_32x32x16_bf16 v[0:15], v[132:135], v[140:143], v[0:15]
	ds_read_b128 v[132:135], v128 offset:36960
	ds_read_b128 v[136:139], v129 offset:55392
	ds_read_b128 v[140:143], v129 offset:60000
	s_waitcnt lgkmcnt(1)
	v_mfma_f32_32x32x16_bf16 v[48:63], v[132:135], v[136:139], v[48:63]
	s_waitcnt lgkmcnt(0)
	v_mfma_f32_32x32x16_bf16 v[32:47], v[132:135], v[140:143], v[32:47]
	ds_read_b128 v[132:135], v128 offset:41568
	s_setprio 1
	s_waitcnt vmcnt(15)
	ds_write_b128 v130, v[92:95]
	s_waitcnt vmcnt(14)
	ds_write_b128 v130, v[64:67] offset:4608
	s_waitcnt vmcnt(13)
	ds_write_b128 v130, v[68:71] offset:9216
	s_waitcnt vmcnt(12)
	ds_write_b128 v130, v[84:87] offset:13824
	s_waitcnt vmcnt(11)
	ds_write_b128 v130, v[72:75] offset:18432
	s_waitcnt vmcnt(10)
	ds_write_b128 v130, v[76:79] offset:23040
	s_waitcnt vmcnt(9)
	ds_write_b128 v130, v[80:83] offset:27648
	s_waitcnt vmcnt(8)
	ds_write_b128 v130, v[88:91] offset:32256
	s_waitcnt lgkmcnt(0)
	s_barrier
; DI void gemm_128_deep(const bf16_t* __restrict__ A, int lda, const bf16_t* __restrict__ B, int ldb, int K, f32x16 (&acc)[2][2], bf16_t* sA, bf16_t* sBunused) {
;     ...
;   MMA_TILE(1)
;   ST_LDS(0, pa0, pa1, pa2, pa3, pb0, pb1, pb2, pb3)
;   __syncthreads();
;   MMA_TILE(0)
;   ST_LDS(1, qa0, qa1, qa2, qa3, qb0, qb1, qb2, qb3)
;   __syncthreads();
;   MMA_TILE(1)
;   __syncthreads();
	s_setprio 2
	ds_read_b128 v[64:67], v128
	ds_read_b128 v[68:71], v129 offset:18432
	ds_read_b128 v[72:75], v129 offset:23040
	s_waitcnt lgkmcnt(1)
	v_mfma_f32_32x32x16_bf16 v[48:63], v[64:67], v[68:71], v[48:63]
	s_waitcnt lgkmcnt(0)
	v_mfma_f32_32x32x16_bf16 v[32:47], v[64:67], v[72:75], v[32:47]
	ds_read_b128 v[64:67], v128 offset:4608
	v_mfma_f32_32x32x16_bf16 v[16:31], v[132:135], v[136:139], v[16:31]
	v_mfma_f32_32x32x16_bf16 v[0:15], v[132:135], v[140:143], v[0:15]
	s_waitcnt lgkmcnt(0)
	v_mfma_f32_32x32x16_bf16 v[16:31], v[64:67], v[68:71], v[16:31]
	v_mfma_f32_32x32x16_bf16 v[0:15], v[64:67], v[72:75], v[0:15]
	ds_read_b128 v[64:67], v128 offset:32
	ds_read_b128 v[68:71], v129 offset:18464
	ds_read_b128 v[72:75], v129 offset:23072
	s_waitcnt lgkmcnt(1)
	v_mfma_f32_32x32x16_bf16 v[48:63], v[64:67], v[68:71], v[48:63]
	s_waitcnt lgkmcnt(0)
	v_mfma_f32_32x32x16_bf16 v[32:47], v[64:67], v[72:75], v[32:47]
	ds_read_b128 v[64:67], v128 offset:4640
	s_waitcnt lgkmcnt(0)
	v_mfma_f32_32x32x16_bf16 v[16:31], v[64:67], v[68:71], v[16:31]
	v_mfma_f32_32x32x16_bf16 v[0:15], v[64:67], v[72:75], v[0:15]
	ds_read_b128 v[64:67], v128 offset:64
	ds_read_b128 v[68:71], v129 offset:18496
	ds_read_b128 v[72:75], v129 offset:23104
	s_waitcnt lgkmcnt(1)
	v_mfma_f32_32x32x16_bf16 v[48:63], v[64:67], v[68:71], v[48:63]
	s_waitcnt lgkmcnt(0)
	v_mfma_f32_32x32x16_bf16 v[32:47], v[64:67], v[72:75], v[32:47]
	ds_read_b128 v[64:67], v128 offset:4672
	s_waitcnt lgkmcnt(0)
	v_mfma_f32_32x32x16_bf16 v[16:31], v[64:67], v[68:71], v[16:31]
	v_mfma_f32_32x32x16_bf16 v[0:15], v[64:67], v[72:75], v[0:15]
	ds_read_b128 v[64:67], v128 offset:96
	ds_read_b128 v[68:71], v129 offset:18528
	ds_read_b128 v[72:75], v129 offset:23136
	s_waitcnt lgkmcnt(1)
	v_mfma_f32_32x32x16_bf16 v[48:63], v[64:67], v[68:71], v[48:63]
	s_waitcnt lgkmcnt(0)
	v_mfma_f32_32x32x16_bf16 v[32:47], v[64:67], v[72:75], v[32:47]
	ds_read_b128 v[64:67], v128 offset:4704
	s_setprio 1
	s_waitcnt vmcnt(7)
	ds_write_b128 v130, v[96:99] offset:36864
	s_waitcnt vmcnt(6)
	ds_write_b128 v130, v[100:103] offset:41472
	s_waitcnt vmcnt(5)
	ds_write_b128 v130, v[104:107] offset:46080
	s_waitcnt vmcnt(4)
	ds_write_b128 v130, v[108:111] offset:50688
	s_waitcnt vmcnt(3)
	ds_write_b128 v130, v[112:115] offset:55296
	s_waitcnt vmcnt(2)
	ds_write_b128 v130, v[116:119] offset:59904
	s_waitcnt vmcnt(1)
	ds_write_b128 v130, v[120:123] offset:64512
	s_waitcnt vmcnt(0)
	ds_write_b128 v131, v[124:127] offset:13824
	s_waitcnt lgkmcnt(0)
	s_barrier
	s_setprio 2
	v_mfma_f32_32x32x16_bf16 v[16:31], v[64:67], v[68:71], v[16:31]
	v_mfma_f32_32x32x16_bf16 v[0:15], v[64:67], v[72:75], v[0:15]
	ds_read_b128 v[64:67], v128 offset:36864
	ds_read_b128 v[68:71], v129 offset:55296
	ds_read_b128 v[72:75], v129 offset:59904
	s_waitcnt lgkmcnt(1)
	v_mfma_f32_32x32x16_bf16 v[48:63], v[64:67], v[68:71], v[48:63]
	s_waitcnt lgkmcnt(0)
	v_mfma_f32_32x32x16_bf16 v[32:47], v[64:67], v[72:75], v[32:47]
	ds_read_b128 v[64:67], v128 offset:41472
	s_waitcnt lgkmcnt(0)
	v_mfma_f32_32x32x16_bf16 v[16:31], v[64:67], v[68:71], v[16:31]
	v_mfma_f32_32x32x16_bf16 v[0:15], v[64:67], v[72:75], v[0:15]
	ds_read_b128 v[64:67], v128 offset:36896
	ds_read_b128 v[68:71], v129 offset:55328
	ds_read_b128 v[72:75], v129 offset:59936
	s_waitcnt lgkmcnt(1)
	v_mfma_f32_32x32x16_bf16 v[48:63], v[64:67], v[68:71], v[48:63]
	s_waitcnt lgkmcnt(0)
	v_mfma_f32_32x32x16_bf16 v[32:47], v[64:67], v[72:75], v[32:47]
	ds_read_b128 v[64:67], v128 offset:41504
	s_waitcnt lgkmcnt(0)
	v_mfma_f32_32x32x16_bf16 v[16:31], v[64:67], v[68:71], v[16:31]
	v_mfma_f32_32x32x16_bf16 v[0:15], v[64:67], v[72:75], v[0:15]
	ds_read_b128 v[64:67], v128 offset:36928
	ds_read_b128 v[68:71], v129 offset:55360
	ds_read_b128 v[72:75], v129 offset:59968
	s_waitcnt lgkmcnt(1)
	v_mfma_f32_32x32x16_bf16 v[48:63], v[64:67], v[68:71], v[48:63]
	s_waitcnt lgkmcnt(0)
	v_mfma_f32_32x32x16_bf16 v[32:47], v[64:67], v[72:75], v[32:47]
	ds_read_b128 v[64:67], v128 offset:41536
	s_waitcnt lgkmcnt(0)
	v_mfma_f32_32x32x16_bf16 v[16:31], v[64:67], v[68:71], v[16:31]
	v_mfma_f32_32x32x16_bf16 v[0:15], v[64:67], v[72:75], v[0:15]
	ds_read_b128 v[64:67], v128 offset:36960
	ds_read_b128 v[68:71], v129 offset:55392
	ds_read_b128 v[72:75], v129 offset:60000
	s_waitcnt lgkmcnt(1)
	v_mfma_f32_32x32x16_bf16 v[48:63], v[64:67], v[68:71], v[48:63]
	s_waitcnt lgkmcnt(0)
	v_mfma_f32_32x32x16_bf16 v[32:47], v[64:67], v[72:75], v[32:47]
	ds_read_b128 v[64:67], v128 offset:41568
	s_waitcnt lgkmcnt(0)
	s_barrier
	s_setprio 2
	v_mfma_f32_32x32x16_bf16 v[16:31], v[64:67], v[68:71], v[16:31]
	v_mfma_f32_32x32x16_bf16 v[0:15], v[64:67], v[72:75], v[0:15]
	s_setprio 0
	s_cbranch_scc1 .LBB0_213
	s_andn2_b64 vcc, exec, s[52:53]
	s_cbranch_vccz .LBB0_225

; DI void gemm_128_2set(const bf16_t* __restrict__ A, int lda, const bf16_t* __restrict__ B, int ldb, int K, f32x16 (&acc)[2][2], bf16_t* sA, bf16_t* sB) {
;     ...
;   GL2_P(0)
;   GL2_Q(64)
;   for (int k0 = 0; k0 < K - 128; k0 += 128) {
;     __syncthreads();
;     ST2(pa0, pa1, pa2, pa3, pb0, pb1, pb2, pb3)
;     __syncthreads();
;     GL2_P(k0 + 128)
;     MMA2()
;     __syncthreads();
;     ST2(qa0, qa1, qa2, qa3, qb0, qb1, qb2, qb3)
;     __syncthreads();
;     GL2_Q(k0 + 192)
.LBB0_881:
	s_barrier
	s_setprio 2
	s_setprio 1
	s_waitcnt vmcnt(12)
	ds_write_b128 v184, v[108:111]
	ds_write_b128 v184, v[96:99] offset:4608
	ds_write_b128 v184, v[100:103] offset:9216
	ds_write_b128 v184, v[104:107] offset:13824
	s_waitcnt vmcnt(11)
	ds_write_b128 v184, v[112:115] offset:18432
	s_waitcnt vmcnt(10)
	ds_write_b128 v184, v[116:119] offset:23040
	s_waitcnt vmcnt(9)
	ds_write_b128 v184, v[120:123] offset:27648
	s_waitcnt vmcnt(8)
	ds_write_b128 v184, v[124:127] offset:32256
	s_waitcnt lgkmcnt(0)
	s_barrier
	s_setprio 2
	ds_read_b128 v[96:99], v128
	ds_read_b128 v[100:103], v129 offset:18432
	ds_read_b128 v[104:107], v128 offset:32
	ds_read_b128 v[108:111], v129 offset:18464
	ds_read_b128 v[112:115], v129 offset:23040
	ds_read_b128 v[116:119], v129 offset:23072
	s_waitcnt lgkmcnt(4)
	v_mfma_f32_32x32x16_bf16 v[48:63], v[96:99], v[100:103], v[48:63]
	s_mov_b32 s55, 0x19864000
	v_lshl_add_u64 v[202:203], v[130:131], 0, v[156:157]
	v_lshl_add_u64 v[204:205], v[138:139], 0, v[156:157]
	v_lshl_add_u64 v[206:207], v[134:135], 0, v[156:157]
	v_lshl_add_u64 v[208:209], v[136:137], 0, v[156:157]
	s_addk_i32 s54, 0x80
	v_lshl_add_u64 v[130:131], v[130:131], 0, s[94:95]
	s_waitcnt lgkmcnt(1)
	v_mfma_f32_32x32x16_bf16 v[32:47], v[96:99], v[112:115], v[32:47]
	ds_read_b128 v[96:99], v128 offset:4608
	ds_read_b128 v[120:123], v128 offset:4640
	v_lshl_add_u64 v[134:135], v[134:135], 0, s[94:95]
	v_lshl_add_u64 v[136:137], v[136:137], 0, s[94:95]
	s_cmpk_lt_u32 s54, 0x100
	v_lshl_add_u64 v[138:139], v[138:139], 0, s[94:95]
	s_waitcnt lgkmcnt(1)
	v_mfma_f32_32x32x16_bf16 v[16:31], v[96:99], v[100:103], v[16:31]
	v_mfma_f32_32x32x16_bf16 v[0:15], v[96:99], v[112:115], v[0:15]
	ds_read_b128 v[96:99], v128 offset:64
	ds_read_b128 v[100:103], v129 offset:18496
	ds_read_b128 v[186:189], v128 offset:96
	ds_read_b128 v[190:193], v129 offset:18528
	v_mfma_f32_32x32x16_bf16 v[48:63], v[104:107], v[108:111], v[48:63]
	v_mfma_f32_32x32x16_bf16 v[32:47], v[104:107], v[116:119], v[32:47]
	s_waitcnt lgkmcnt(4)
	v_mfma_f32_32x32x16_bf16 v[16:31], v[120:123], v[108:111], v[16:31]
	v_mfma_f32_32x32x16_bf16 v[0:15], v[120:123], v[116:119], v[0:15]
	ds_read_b128 v[112:115], v129 offset:23104
	ds_read_b128 v[116:119], v128 offset:4672
	ds_read_b128 v[194:197], v129 offset:23136
	ds_read_b128 v[198:201], v128 offset:4704
	v_lshl_add_u64 v[120:121], v[132:133], 0, v[156:157]
	v_add_co_u32_e32 v210, vcc, s55, v120
	s_mov_b32 s55, 0x1986c000
	s_nop 0
	v_addc_co_u32_e32 v211, vcc, 0, v121, vcc
	s_waitcnt lgkmcnt(6)
	v_mfma_f32_32x32x16_bf16 v[48:63], v[96:99], v[100:103], v[48:63]
	v_add_co_u32_e32 v212, vcc, s55, v120
	s_mov_b32 s55, 0x19874000
	s_nop 0
	v_addc_co_u32_e32 v213, vcc, 0, v121, vcc
	v_add_co_u32_e32 v226, vcc, s55, v120
	s_waitcnt lgkmcnt(3)
	v_mfma_f32_32x32x16_bf16 v[32:47], v[96:99], v[112:115], v[32:47]
	v_addc_co_u32_e32 v227, vcc, 0, v121, vcc
	s_mov_b32 s55, 0x1987c000
	v_add_co_u32_e32 v238, vcc, s55, v120
	global_load_dwordx4 v[108:111], v[202:203], off offset:256
	s_nop 0
	v_addc_co_u32_e32 v239, vcc, 0, v121, vcc
	s_waitcnt lgkmcnt(2)
	v_mfma_f32_32x32x16_bf16 v[16:31], v[116:119], v[100:103], v[16:31]
	global_load_dwordx4 v[96:99], v[204:205], off offset:256
	global_load_dwordx4 v[100:103], v[206:207], off offset:256
	global_load_dwordx4 v[104:107], v[208:209], off offset:256
	v_lshl_add_u64 v[132:133], v[132:133], 0, s[94:95]
	v_mfma_f32_32x32x16_bf16 v[0:15], v[116:119], v[112:115], v[0:15]
	global_load_dwordx4 v[112:115], v[210:211], off offset:2048
	global_load_dwordx4 v[116:119], v[212:213], off offset:2048
	global_load_dwordx4 v[120:123], v[226:227], off offset:2048
	global_load_dwordx4 v[124:127], v[238:239], off offset:2048
	s_waitcnt lgkmcnt(0)
	s_barrier
	s_setprio 2
	s_setprio 1
	s_waitcnt vmcnt(15)
	ds_write_b128 v184, v[64:67]
	s_waitcnt vmcnt(14)
	ds_write_b128 v184, v[68:71] offset:4608
	s_waitcnt vmcnt(13)
	ds_write_b128 v184, v[72:75] offset:9216
	s_waitcnt vmcnt(12)
	ds_write_b128 v184, v[80:83] offset:13824
	s_waitcnt vmcnt(11)
	ds_write_b128 v184, v[76:79] offset:18432
	s_waitcnt vmcnt(10)
	ds_write_b128 v184, v[84:87] offset:23040
	s_waitcnt vmcnt(9)
	ds_write_b128 v184, v[88:91] offset:27648
	s_waitcnt vmcnt(8)
	ds_write_b128 v184, v[92:95] offset:32256
	s_waitcnt lgkmcnt(0)
	v_mfma_f32_32x32x16_bf16 v[48:63], v[186:189], v[190:193], v[48:63]
	s_barrier
; DI void gemm_128_2set(const bf16_t* __restrict__ A, int lda, const bf16_t* __restrict__ B, int ldb, int K, f32x16 (&acc)[2][2], bf16_t* sA, bf16_t* sB) {
;     ...
;   for (int k0 = 0; k0 < K - 128; k0 += 128) {
;     __syncthreads();
;     ST2(pa0, pa1, pa2, pa3, pb0, pb1, pb2, pb3)
;     __syncthreads();
;     GL2_P(k0 + 128)
;     MMA2()
;     __syncthreads();
;     ST2(qa0, qa1, qa2, qa3, qb0, qb1, qb2, qb3)
;     __syncthreads();
;     GL2_Q(k0 + 192)
;     MMA2()
;   }
;   __syncthreads();
;   ST2(pa0, pa1, pa2, pa3, pb0, pb1, pb2, pb3)
;   __syncthreads();
;   MMA2()
;   __syncthreads();
;   ST2(qa0, qa1, qa2, qa3, qb0, qb1, qb2, qb3)
;   __syncthreads();
;   MMA2()
	s_setprio 2
	ds_read_b128 v[64:67], v128
	ds_read_b128 v[68:71], v129 offset:18432
	ds_read_b128 v[72:75], v128 offset:32
	ds_read_b128 v[76:79], v129 offset:18464
	ds_read_b128 v[80:83], v129 offset:23040
	ds_read_b128 v[84:87], v129 offset:23072
	v_mfma_f32_32x32x16_bf16 v[32:47], v[186:189], v[194:197], v[32:47]
	v_mfma_f32_32x32x16_bf16 v[16:31], v[198:201], v[190:193], v[16:31]
	v_mfma_f32_32x32x16_bf16 v[0:15], v[198:201], v[194:197], v[0:15]
	s_waitcnt lgkmcnt(4)
	v_mfma_f32_32x32x16_bf16 v[48:63], v[64:67], v[68:71], v[48:63]
	s_waitcnt lgkmcnt(1)
	v_mfma_f32_32x32x16_bf16 v[32:47], v[64:67], v[80:83], v[32:47]
	ds_read_b128 v[64:67], v128 offset:4608
	ds_read_b128 v[88:91], v128 offset:4640
	s_waitcnt lgkmcnt(1)
	v_mfma_f32_32x32x16_bf16 v[16:31], v[64:67], v[68:71], v[16:31]
	v_mfma_f32_32x32x16_bf16 v[0:15], v[64:67], v[80:83], v[0:15]
	v_mfma_f32_32x32x16_bf16 v[48:63], v[72:75], v[76:79], v[48:63]
	v_mfma_f32_32x32x16_bf16 v[32:47], v[72:75], v[84:87], v[32:47]
	ds_read_b128 v[64:67], v128 offset:64
	ds_read_b128 v[68:71], v129 offset:18496
	ds_read_b128 v[72:75], v128 offset:96
	ds_read_b128 v[92:95], v129 offset:18528
	s_waitcnt lgkmcnt(4)
	v_mfma_f32_32x32x16_bf16 v[16:31], v[88:91], v[76:79], v[16:31]
	ds_read_b128 v[76:79], v129 offset:23104
	ds_read_b128 v[186:189], v129 offset:23136
	v_mfma_f32_32x32x16_bf16 v[0:15], v[88:91], v[84:87], v[0:15]
	s_waitcnt lgkmcnt(4)
	v_mfma_f32_32x32x16_bf16 v[48:63], v[64:67], v[68:71], v[48:63]
	s_waitcnt lgkmcnt(1)
	v_mfma_f32_32x32x16_bf16 v[32:47], v[64:67], v[76:79], v[32:47]
	ds_read_b128 v[64:67], v128 offset:4672
	ds_read_b128 v[190:193], v128 offset:4704
	s_waitcnt lgkmcnt(1)
	v_mfma_f32_32x32x16_bf16 v[16:31], v[64:67], v[68:71], v[16:31]
	v_mfma_f32_32x32x16_bf16 v[0:15], v[64:67], v[76:79], v[0:15]
	v_mfma_f32_32x32x16_bf16 v[48:63], v[72:75], v[92:95], v[48:63]
	v_mfma_f32_32x32x16_bf16 v[32:47], v[72:75], v[186:189], v[32:47]
	global_load_dwordx4 v[64:67], v[202:203], off offset:384
	global_load_dwordx4 v[68:71], v[204:205], off offset:384
	global_load_dwordx4 v[72:75], v[206:207], off offset:384
	global_load_dwordx4 v[80:83], v[208:209], off offset:384
	global_load_dwordx4 v[76:79], v[210:211], off offset:2176
	global_load_dwordx4 v[84:87], v[212:213], off offset:2176
	global_load_dwordx4 v[88:91], v[226:227], off offset:2176
	s_waitcnt lgkmcnt(0)
	v_mfma_f32_32x32x16_bf16 v[16:31], v[190:193], v[92:95], v[16:31]
	global_load_dwordx4 v[92:95], v[238:239], off offset:2176
	v_mfma_f32_32x32x16_bf16 v[0:15], v[190:193], v[186:189], v[0:15]
	s_cbranch_scc1 .LBB0_881
	s_barrier
	s_setprio 2
	s_setprio 1
	s_waitcnt vmcnt(15)
	ds_write_b128 v184, v[108:111]
	s_waitcnt vmcnt(14)
	ds_write_b128 v184, v[96:99] offset:4608
	s_waitcnt vmcnt(13)
	ds_write_b128 v184, v[100:103] offset:9216
	s_waitcnt vmcnt(12)
	ds_write_b128 v184, v[104:107] offset:13824
	s_waitcnt vmcnt(11)
	ds_write_b128 v184, v[112:115] offset:18432
	s_waitcnt vmcnt(10)
	ds_write_b128 v184, v[116:119] offset:23040
	s_waitcnt vmcnt(9)
	ds_write_b128 v184, v[120:123] offset:27648
	s_waitcnt vmcnt(8)
	ds_write_b128 v184, v[124:127] offset:32256
	s_waitcnt lgkmcnt(0)
	s_barrier
	s_setprio 2
	ds_read_b128 v[96:99], v128
	ds_read_b128 v[100:103], v129 offset:18432
	ds_read_b128 v[104:107], v128 offset:32
	ds_read_b128 v[108:111], v129 offset:18464
	ds_read_b128 v[112:115], v129 offset:23040
	ds_read_b128 v[116:119], v129 offset:23072
	s_waitcnt lgkmcnt(4)
	v_mfma_f32_32x32x16_bf16 v[48:63], v[96:99], v[100:103], v[48:63]
	s_lshl_b64 s[54:55], s[50:51], 12
	s_lshl_b64 s[52:53], s[52:53], 12
	s_add_u32 s52, s63, s52
	s_addc_u32 s53, s64, s53
	s_movk_i32 s51, 0xff80
	s_waitcnt lgkmcnt(1)
	v_mfma_f32_32x32x16_bf16 v[32:47], v[96:99], v[112:115], v[32:47]
	ds_read_b128 v[96:99], v128 offset:4608
	ds_read_b128 v[120:123], v128 offset:4640
	s_waitcnt lgkmcnt(1)
	v_mfma_f32_32x32x16_bf16 v[16:31], v[96:99], v[100:103], v[16:31]
	v_mfma_f32_32x32x16_bf16 v[0:15], v[96:99], v[112:115], v[0:15]
	v_mfma_f32_32x32x16_bf16 v[48:63], v[104:107], v[108:111], v[48:63]
	v_mfma_f32_32x32x16_bf16 v[32:47], v[104:107], v[116:119], v[32:47]
	s_waitcnt lgkmcnt(0)
	v_mfma_f32_32x32x16_bf16 v[16:31], v[120:123], v[108:111], v[16:31]
	ds_read_b128 v[96:99], v128 offset:64
	ds_read_b128 v[100:103], v129 offset:18496
	ds_read_b128 v[104:107], v128 offset:96
	ds_read_b128 v[108:111], v129 offset:18528
	v_mfma_f32_32x32x16_bf16 v[0:15], v[120:123], v[116:119], v[0:15]
	ds_read_b128 v[112:115], v129 offset:23104
	ds_read_b128 v[116:119], v129 offset:23136
	s_waitcnt lgkmcnt(4)
	v_mfma_f32_32x32x16_bf16 v[48:63], v[96:99], v[100:103], v[48:63]
	s_waitcnt lgkmcnt(1)
	v_mfma_f32_32x32x16_bf16 v[32:47], v[96:99], v[112:115], v[32:47]
	ds_read_b128 v[96:99], v128 offset:4672
	ds_read_b128 v[120:123], v128 offset:4704
	s_waitcnt lgkmcnt(0)
	s_barrier
	s_setprio 2
	s_setprio 1
	s_waitcnt vmcnt(7)
	ds_write_b128 v184, v[64:67]
	s_waitcnt vmcnt(6)
	ds_write_b128 v184, v[68:71] offset:4608
	s_waitcnt vmcnt(5)
	ds_write_b128 v184, v[72:75] offset:9216
	s_waitcnt vmcnt(4)
	ds_write_b128 v184, v[80:83] offset:13824
	s_waitcnt vmcnt(3)
	ds_write_b128 v184, v[76:79] offset:18432
	s_waitcnt vmcnt(2)
	ds_write_b128 v184, v[84:87] offset:23040
	s_waitcnt vmcnt(1)
	ds_write_b128 v184, v[88:91] offset:27648
	s_waitcnt vmcnt(0)
	ds_write_b128 v184, v[92:95] offset:32256
	s_waitcnt lgkmcnt(0)
	v_mfma_f32_32x32x16_bf16 v[16:31], v[96:99], v[100:103], v[16:31]
	s_barrier
; DI void gemm_128_2set(const bf16_t* __restrict__ A, int lda, const bf16_t* __restrict__ B, int ldb, int K, f32x16 (&acc)[2][2], bf16_t* sA, bf16_t* sB) {
;     ...
;   const bf16_t* ga = A + (size_t)lrow * lda + lkc;
;   const bf16_t* gb = B + (size_t)lrow * ldb + lkc;
;   uint4 pa0, pa1, pa2, pa3, pb0, pb1, pb2, pb3, qa0, qa1, qa2, qa3, qb0, qb1, qb2, qb3;
;     ...
;   GL2_P(0)
;   GL2_Q(64)
; DI void phase_merge(CP p, const Ptrs& w, int l, bf16_t* sA, bf16_t* sB, unsigned* sU) {
;     ...
;         zero_acc(U);
;         gemm_128_2set(ys + (size_t)m0 * lds_, lds_, up_t + (size_t)(br * 2048 + n0) * 512, 512, 512, U, sA, sB);
; #pragma unroll
;         for (int a = 0; a < 2; ++a)
; #pragma unroll
;           for (int c = 0; c < 2; ++c)
; #pragma unroll
;             for (int i = 0; i < 8; ++i) sU[((a * 2 + c) * 8 + i) * 256 + tid] = pack2(U[a][c][2 * i], U[a][c][2 * i + 1]);
;       }
;       f32x16 G[2][2];
;       zero_acc(G);
;       gemm_128_2set(w.H + (size_t)m0 * 2048, 2048, gate_t + (size_t)(br * 2048 + n0) * 2048, 2048, 2048, G, sA, sB);
	s_setprio 2
	ds_read_b128 v[64:67], v128
	ds_read_b128 v[68:71], v129 offset:18432
	ds_read_b128 v[72:75], v128 offset:32
	ds_read_b128 v[76:79], v129 offset:18464
	ds_read_b128 v[80:83], v129 offset:23040
	ds_read_b128 v[84:87], v129 offset:23072
	v_mfma_f32_32x32x16_bf16 v[0:15], v[96:99], v[112:115], v[0:15]
	v_mfma_f32_32x32x16_bf16 v[48:63], v[104:107], v[108:111], v[48:63]
	v_mfma_f32_32x32x16_bf16 v[32:47], v[104:107], v[116:119], v[32:47]
	v_mfma_f32_32x32x16_bf16 v[16:31], v[120:123], v[108:111], v[16:31]
	v_mfma_f32_32x32x16_bf16 v[0:15], v[120:123], v[116:119], v[0:15]
	s_waitcnt lgkmcnt(4)
	v_mfma_f32_32x32x16_bf16 v[48:63], v[64:67], v[68:71], v[48:63]
	s_waitcnt lgkmcnt(1)
	v_mfma_f32_32x32x16_bf16 v[32:47], v[64:67], v[80:83], v[32:47]
	ds_read_b128 v[64:67], v128 offset:4608
	ds_read_b128 v[88:91], v128 offset:4640
	s_waitcnt lgkmcnt(1)
	v_mfma_f32_32x32x16_bf16 v[16:31], v[64:67], v[68:71], v[16:31]
	v_mfma_f32_32x32x16_bf16 v[0:15], v[64:67], v[80:83], v[0:15]
	v_mfma_f32_32x32x16_bf16 v[48:63], v[72:75], v[76:79], v[48:63]
	v_mfma_f32_32x32x16_bf16 v[32:47], v[72:75], v[84:87], v[32:47]
	s_waitcnt lgkmcnt(0)
	v_mfma_f32_32x32x16_bf16 v[16:31], v[88:91], v[76:79], v[16:31]
	ds_read_b128 v[64:67], v128 offset:64
	ds_read_b128 v[68:71], v129 offset:18496
	ds_read_b128 v[72:75], v128 offset:96
	ds_read_b128 v[76:79], v129 offset:18528
	v_mfma_f32_32x32x16_bf16 v[0:15], v[88:91], v[84:87], v[0:15]
	ds_read_b128 v[80:83], v129 offset:23104
	ds_read_b128 v[84:87], v128 offset:4672
	ds_read_b128 v[88:91], v128 offset:4704
	ds_read_b128 v[92:95], v129 offset:23136
	s_waitcnt lgkmcnt(6)
	v_mfma_f32_32x32x16_bf16 v[48:63], v[64:67], v[68:71], v[48:63]
	s_waitcnt lgkmcnt(3)
	v_mfma_f32_32x32x16_bf16 v[32:47], v[64:67], v[80:83], v[32:47]
	s_waitcnt lgkmcnt(2)
	v_mfma_f32_32x32x16_bf16 v[16:31], v[84:87], v[68:71], v[16:31]
	v_mfma_f32_32x32x16_bf16 v[0:15], v[84:87], v[80:83], v[0:15]
	v_mfma_f32_32x32x16_bf16 v[48:63], v[72:75], v[76:79], v[48:63]
	s_waitcnt lgkmcnt(0)
	v_mfma_f32_32x32x16_bf16 v[32:47], v[72:75], v[92:95], v[32:47]
	s_nop 9
	v_cvt_pk_bf16_f32 v48, v48, v49
	v_cvt_pk_bf16_f32 v49, v50, v51
	ds_write2st64_b32 v140, v48, v49 offset0:144 offset1:148
	v_cvt_pk_bf16_f32 v48, v52, v53
	v_cvt_pk_bf16_f32 v49, v54, v55
	ds_write2st64_b32 v140, v48, v49 offset0:152 offset1:156
	v_cvt_pk_bf16_f32 v48, v56, v57
	v_mfma_f32_32x32x16_bf16 v[16:31], v[88:91], v[76:79], v[16:31]
	v_cvt_pk_bf16_f32 v32, v32, v33
	v_cvt_pk_bf16_f32 v33, v34, v35
	ds_write2st64_b32 v140, v32, v33 offset0:176 offset1:180
	v_cvt_pk_bf16_f32 v32, v36, v37
	v_cvt_pk_bf16_f32 v33, v38, v39
	v_cvt_pk_bf16_f32 v49, v58, v59
	ds_write2st64_b32 v140, v32, v33 offset0:184 offset1:188
	v_mfma_f32_32x32x16_bf16 v[0:15], v[88:91], v[92:95], v[0:15]
	s_setprio 0
	s_nop 3
	v_cvt_pk_bf16_f32 v16, v16, v17
	v_cvt_pk_bf16_f32 v17, v18, v19
	ds_write2st64_b32 v140, v16, v17 offset0:208 offset1:212
	v_cvt_pk_bf16_f32 v16, v20, v21
	v_cvt_pk_bf16_f32 v17, v22, v23
	v_cvt_pk_bf16_f32 v32, v40, v41
	v_cvt_pk_bf16_f32 v33, v42, v43
	s_nop 0
	v_cvt_pk_bf16_f32 v0, v0, v1
	v_cvt_pk_bf16_f32 v1, v2, v3
	ds_write2st64_b32 v140, v0, v1 offset0:240 offset1:244
	v_cvt_pk_bf16_f32 v0, v4, v5
	v_cvt_pk_bf16_f32 v1, v6, v7
	ds_write2st64_b32 v140, v16, v17 offset0:216 offset1:220
	v_cvt_pk_bf16_f32 v16, v24, v25
	v_cvt_pk_bf16_f32 v17, v26, v27
	ds_write2st64_b32 v140, v0, v1 offset0:248 offset1:252
	v_cvt_pk_bf16_f32 v0, v8, v9
	v_cvt_pk_bf16_f32 v1, v10, v11
	ds_write2st64_b32 v140, v48, v49 offset0:160 offset1:164
	v_cvt_pk_bf16_f32 v48, v60, v61
	v_cvt_pk_bf16_f32 v49, v62, v63
	ds_write2st64_b32 v140, v32, v33 offset0:192 offset1:196
	v_cvt_pk_bf16_f32 v32, v44, v45
	v_cvt_pk_bf16_f32 v33, v46, v47
	ds_write2st64_b32 v140, v16, v17 offset0:224 offset1:228
	v_cvt_pk_bf16_f32 v16, v28, v29
	v_cvt_pk_bf16_f32 v17, v30, v31
	ds_write2st64_b32 v141, v0, v1 offset0:112 offset1:116
	v_cvt_pk_bf16_f32 v0, v12, v13
	v_cvt_pk_bf16_f32 v1, v14, v15
	v_mov_b32_e32 v20, v214
	ds_write2st64_b32 v140, v48, v49 offset0:168 offset1:172
	ds_write2st64_b32 v140, v32, v33 offset0:200 offset1:204
	ds_write2st64_b32 v140, v16, v17 offset0:232 offset1:236
	ds_write2st64_b32 v141, v0, v1 offset0:120 offset1:124
	s_nop 0
	v_ashrrev_i32_e32 v0, 3, v20
	v_lshlrev_b32_e32 v1, 3, v20
	v_and_b32_e32 v6, 56, v1
	v_ashrrev_i32_e32 v1, 31, v0
	v_lshlrev_b64 v[2:3], 12, v[0:1]
	v_lshl_add_u64 v[4:5], s[40:41], 0, v[2:3]
	v_lshlrev_b32_e32 v156, 1, v6
	v_lshl_add_u64 v[4:5], v[4:5], 0, v[156:157]
	v_add_co_u32_e32 v8, vcc, s75, v4
	v_lshl_add_u64 v[6:7], s[52:53], 0, v[2:3]
	s_nop 0
	v_addc_co_u32_e32 v9, vcc, 0, v5, vcc
	v_add_co_u32_e32 v10, vcc, s80, v4
	v_lshl_add_u64 v[6:7], v[6:7], 0, v[156:157]
	s_nop 0
	v_addc_co_u32_e32 v11, vcc, 0, v5, vcc
	v_add_co_u32_e32 v12, vcc, s28, v4
	v_mul_lo_u32 v0, v0, s88
	s_nop 0
	v_addc_co_u32_e32 v13, vcc, 0, v5, vcc
	v_add_co_u32_e32 v14, vcc, s75, v6
	v_and_b32_e32 v1, 31, v20
	s_nop 0
	v_addc_co_u32_e32 v15, vcc, 0, v7, vcc
	v_add_co_u32_e32 v16, vcc, s80, v6
	v_lshl_add_u32 v134, v0, 1, v156
	s_nop 0
	v_addc_co_u32_e32 v17, vcc, 0, v7, vcc
	v_add_co_u32_e32 v18, vcc, s28, v6
	v_lshrrev_b32_e32 v0, 1, v20
	s_nop 0
	v_addc_co_u32_e32 v19, vcc, 0, v7, vcc
	global_load_dwordx4 v[96:99], v[4:5], off
	global_load_dwordx4 v[80:83], v[4:5], off offset:128
	global_load_dwordx4 v[100:103], v[8:9], off
	global_load_dwordx4 v[64:67], v[8:9], off offset:128
	global_load_dwordx4 v[104:107], v[10:11], off
	global_load_dwordx4 v[68:71], v[10:11], off offset:128
	global_load_dwordx4 v[108:111], v[12:13], off
	global_load_dwordx4 v[72:75], v[12:13], off offset:128
; DI void gemm_128_2set(const bf16_t* __restrict__ A, int lda, const bf16_t* __restrict__ B, int ldb, int K, f32x16 (&acc)[2][2], bf16_t* sA, bf16_t* sB) {
;     ...
;   GL2_P(0)
;   GL2_Q(64)
;   for (int k0 = 0; k0 < K - 128; k0 += 128) {
;     __syncthreads();
;     ST2(pa0, pa1, pa2, pa3, pb0, pb1, pb2, pb3)
;     __syncthreads();
;     GL2_P(k0 + 128)
;     MMA2()
; DI void phase_merge(CP p, const Ptrs& w, int l, bf16_t* sA, bf16_t* sB, unsigned* sU) {
;     ...
;       f32x16 G[2][2];
;       zero_acc(G);
;       gemm_128_2set(w.H + (size_t)m0 * 2048, 2048, gate_t + (size_t)(br * 2048 + n0) * 2048, 2048, 2048, G, sA, sB);
	global_load_dwordx4 v[112:115], v[6:7], off
	global_load_dwordx4 v[76:79], v[6:7], off offset:128
	global_load_dwordx4 v[116:119], v[14:15], off
	global_load_dwordx4 v[84:87], v[14:15], off offset:128
	global_load_dwordx4 v[120:123], v[16:17], off
	global_load_dwordx4 v[88:91], v[16:17], off offset:128
	global_load_dwordx4 v[124:127], v[18:19], off
	global_load_dwordx4 v[92:95], v[18:19], off offset:128
	v_and_or_b32 v1, v0, s82, v1
	v_and_b32_e32 v0, 16, v0
	v_mad_u64_u32 v[128:129], s[52:53], v1, s81, v[0:1]
	v_and_b32_e32 v1, 0x5f, v20
	v_mad_u32_u24 v129, v1, s81, v0
	v_and_b32_e32 v0, 7, v20
	s_add_u32 s52, s2, s54
	v_lshlrev_b32_e32 v156, 4, v0
	s_addc_u32 s53, s3, s55
	v_mov_b32_e32 v0, 0
	v_lshl_add_u64 v[130:131], s[52:53], 0, v[2:3]
	v_lshl_add_u64 v[132:133], s[48:49], 0, v[2:3]
	v_mov_b32_e32 v1, v0
	v_mov_b32_e32 v2, v0
	v_mov_b32_e32 v3, v0
	v_mov_b32_e32 v4, v0
	v_mov_b32_e32 v5, v0
	v_mov_b32_e32 v6, v0
	v_mov_b32_e32 v7, v0
	v_mov_b32_e32 v8, v0
	v_mov_b32_e32 v9, v0
	v_mov_b32_e32 v10, v0
	v_mov_b32_e32 v11, v0
	v_mov_b32_e32 v12, v0
	v_mov_b32_e32 v13, v0
	v_mov_b32_e32 v14, v0
	v_mov_b32_e32 v15, v0
	v_mov_b32_e32 v16, v0
	v_mov_b32_e32 v17, v0
	v_mov_b32_e32 v18, v0
	v_mov_b32_e32 v19, v0
	v_mov_b32_e32 v20, v0
	v_mov_b32_e32 v21, v0
	v_mov_b32_e32 v22, v0
	v_mov_b32_e32 v23, v0
	v_mov_b32_e32 v24, v0
	v_mov_b32_e32 v25, v0
	v_mov_b32_e32 v26, v0
	v_mov_b32_e32 v27, v0
	v_mov_b32_e32 v28, v0
	v_mov_b32_e32 v29, v0
	v_mov_b32_e32 v30, v0
	v_mov_b32_e32 v31, v0
	v_mov_b32_e32 v32, v0
	v_mov_b32_e32 v33, v0
	v_mov_b32_e32 v34, v0
	v_mov_b32_e32 v35, v0
	v_mov_b32_e32 v36, v0
	v_mov_b32_e32 v37, v0
	v_mov_b32_e32 v38, v0
	v_mov_b32_e32 v39, v0
	v_mov_b32_e32 v40, v0
	v_mov_b32_e32 v41, v0
	v_mov_b32_e32 v42, v0
	v_mov_b32_e32 v43, v0
	v_mov_b32_e32 v44, v0
	v_mov_b32_e32 v45, v0
	v_mov_b32_e32 v46, v0
	v_mov_b32_e32 v47, v0
	v_mov_b32_e32 v48, v0
	v_mov_b32_e32 v49, v0
	v_mov_b32_e32 v50, v0
	v_mov_b32_e32 v51, v0
	v_mov_b32_e32 v52, v0
	v_mov_b32_e32 v53, v0
	v_mov_b32_e32 v54, v0
	v_mov_b32_e32 v55, v0
	v_mov_b32_e32 v56, v0
	v_mov_b32_e32 v57, v0
	v_mov_b32_e32 v58, v0
	v_mov_b32_e32 v59, v0
	v_mov_b32_e32 v60, v0
	v_mov_b32_e32 v61, v0
	v_mov_b32_e32 v62, v0
	v_mov_b32_e32 v63, v0
	s_setprio 1
	s_waitcnt vmcnt(1)
.LBB0_883:
	s_waitcnt lgkmcnt(0)
	s_barrier
	s_setprio 2
	s_setprio 1
	s_waitcnt vmcnt(15)
	ds_write_b128 v134, v[96:99]
	s_waitcnt vmcnt(14)
	ds_write_b128 v134, v[100:103] offset:4608
	s_waitcnt vmcnt(13)
	ds_write_b128 v134, v[104:107] offset:9216
	s_waitcnt vmcnt(12)
	ds_write_b128 v134, v[108:111] offset:13824
	s_waitcnt vmcnt(11)
	ds_write_b128 v134, v[112:115] offset:18432
	s_waitcnt vmcnt(10)
	ds_write_b128 v134, v[116:119] offset:23040
	s_waitcnt vmcnt(9)
	ds_write_b128 v134, v[120:123] offset:27648
	s_waitcnt vmcnt(8)
	ds_write_b128 v134, v[124:127] offset:32256
	s_waitcnt lgkmcnt(0)
	s_barrier
	s_setprio 2
	ds_read_b128 v[96:99], v128
	ds_read_b128 v[100:103], v129 offset:18432
	ds_read_b128 v[104:107], v128 offset:32
	ds_read_b128 v[108:111], v129 offset:18464
	ds_read_b128 v[112:115], v129 offset:23040
	ds_read_b128 v[116:119], v129 offset:23072
	s_waitcnt lgkmcnt(4)
	v_mfma_f32_32x32x16_bf16 v[48:63], v[96:99], v[100:103], v[48:63]
	s_mov_b32 s52, 0x17864000
	s_addk_i32 s51, 0x80
	s_cmpk_lt_u32 s51, 0x700
	s_waitcnt lgkmcnt(1)
	v_mfma_f32_32x32x16_bf16 v[32:47], v[96:99], v[112:115], v[32:47]
	ds_read_b128 v[96:99], v128 offset:4608
	ds_read_b128 v[120:123], v128 offset:4640
	s_waitcnt lgkmcnt(1)
	v_mfma_f32_32x32x16_bf16 v[16:31], v[96:99], v[100:103], v[16:31]
	v_mfma_f32_32x32x16_bf16 v[0:15], v[96:99], v[112:115], v[0:15]
	v_lshl_add_u64 v[112:113], v[132:133], 0, v[156:157]
	ds_read_b128 v[96:99], v128 offset:4672
	ds_read_b128 v[100:103], v128 offset:64
	ds_read_b128 v[136:139], v128 offset:96
	v_add_co_u32_e32 v196, vcc, s83, v112
	v_lshl_add_u64 v[114:115], v[130:131], 0, v[156:157]
	s_nop 0
	v_addc_co_u32_e32 v197, vcc, 0, v113, vcc
	v_mfma_f32_32x32x16_bf16 v[48:63], v[104:107], v[108:111], v[48:63]
	v_add_co_u32_e32 v198, vcc, s84, v112
	v_lshl_add_u64 v[130:131], v[130:131], 0, s[94:95]
	s_nop 0
	v_addc_co_u32_e32 v199, vcc, 0, v113, vcc
	v_add_co_u32_e32 v200, vcc, s85, v112
	v_mfma_f32_32x32x16_bf16 v[32:47], v[104:107], v[116:119], v[32:47]
	s_nop 0
	v_addc_co_u32_e32 v201, vcc, 0, v113, vcc
	v_add_co_u32_e32 v202, vcc, s86, v112
	v_lshl_add_u64 v[132:133], v[132:133], 0, s[94:95]
	s_nop 0
	v_addc_co_u32_e32 v203, vcc, 0, v113, vcc
	s_waitcnt lgkmcnt(3)
	v_mfma_f32_32x32x16_bf16 v[16:31], v[120:123], v[108:111], v[16:31]
	ds_read_b128 v[184:187], v128 offset:4704
	ds_read_b128 v[104:107], v129 offset:18496
	ds_read_b128 v[188:191], v129 offset:18528
	ds_read_b128 v[108:111], v129 offset:23104
	ds_read_b128 v[192:195], v129 offset:23136
	v_add_co_u32_e32 v204, vcc, s52, v114
	s_mov_b32 s52, 0x17884000
	s_nop 0
	v_addc_co_u32_e32 v205, vcc, 0, v115, vcc
	v_add_co_u32_e32 v206, vcc, s52, v114
	v_mfma_f32_32x32x16_bf16 v[0:15], v[120:123], v[116:119], v[0:15]
	s_nop 0
	v_addc_co_u32_e32 v207, vcc, 0, v115, vcc
	s_mov_b32 s52, 0x178a4000
	v_add_co_u32_e32 v208, vcc, s52, v114
	s_mov_b32 s52, 0x178c4000
	s_nop 0
	v_addc_co_u32_e32 v209, vcc, 0, v115, vcc
	s_waitcnt lgkmcnt(3)
	v_mfma_f32_32x32x16_bf16 v[48:63], v[100:103], v[104:107], v[48:63]
	v_add_co_u32_e32 v210, vcc, s52, v114
	s_nop 1
	v_addc_co_u32_e32 v211, vcc, 0, v115, vcc
	s_waitcnt lgkmcnt(1)
	v_mfma_f32_32x32x16_bf16 v[32:47], v[100:103], v[108:111], v[32:47]
	v_mfma_f32_32x32x16_bf16 v[16:31], v[96:99], v[104:107], v[16:31]
	v_mfma_f32_32x32x16_bf16 v[0:15], v[96:99], v[108:111], v[0:15]
	global_load_dwordx4 v[96:99], v[196:197], off offset:2048
	global_load_dwordx4 v[100:103], v[198:199], off offset:2048
	global_load_dwordx4 v[104:107], v[200:201], off offset:2048
	global_load_dwordx4 v[108:111], v[202:203], off offset:2048
	global_load_dwordx4 v[112:115], v[204:205], off offset:2048
	global_load_dwordx4 v[116:119], v[206:207], off offset:2048
	global_load_dwordx4 v[120:123], v[208:209], off offset:2048
	global_load_dwordx4 v[124:127], v[210:211], off offset:2048
	s_waitcnt lgkmcnt(0)
	s_barrier
; DI void gemm_128_2set(const bf16_t* __restrict__ A, int lda, const bf16_t* __restrict__ B, int ldb, int K, f32x16 (&acc)[2][2], bf16_t* sA, bf16_t* sB) {
;     ...
;     __syncthreads();
;     ST2(qa0, qa1, qa2, qa3, qb0, qb1, qb2, qb3)
;     __syncthreads();
;     GL2_Q(k0 + 192)
;     MMA2()
;   }
;   __syncthreads();
;   ST2(pa0, pa1, pa2, pa3, pb0, pb1, pb2, pb3)
;   __syncthreads();
;   MMA2()
;   __syncthreads();
;   ST2(qa0, qa1, qa2, qa3, qb0, qb1, qb2, qb3)
;   __syncthreads();
	s_setprio 2
	s_setprio 1
	s_waitcnt vmcnt(15)
	ds_write_b128 v134, v[80:83]
	s_waitcnt vmcnt(14)
	ds_write_b128 v134, v[64:67] offset:4608
	s_waitcnt vmcnt(13)
	ds_write_b128 v134, v[68:71] offset:9216
	s_waitcnt vmcnt(12)
	ds_write_b128 v134, v[72:75] offset:13824
	s_waitcnt vmcnt(11)
	ds_write_b128 v134, v[76:79] offset:18432
	s_waitcnt vmcnt(10)
	ds_write_b128 v134, v[84:87] offset:23040
	s_waitcnt vmcnt(9)
	ds_write_b128 v134, v[88:91] offset:27648
	s_waitcnt vmcnt(8)
	ds_write_b128 v134, v[92:95] offset:32256
	v_mfma_f32_32x32x16_bf16 v[48:63], v[136:139], v[188:191], v[48:63]
	s_waitcnt lgkmcnt(0)
	s_barrier
	s_setprio 2
	ds_read_b128 v[64:67], v128
	ds_read_b128 v[68:71], v129 offset:18432
	ds_read_b128 v[72:75], v128 offset:32
	ds_read_b128 v[76:79], v129 offset:18464
	ds_read_b128 v[80:83], v129 offset:23040
	ds_read_b128 v[84:87], v129 offset:23072
	v_mfma_f32_32x32x16_bf16 v[32:47], v[136:139], v[192:195], v[32:47]
	v_mfma_f32_32x32x16_bf16 v[16:31], v[184:187], v[188:191], v[16:31]
	v_mfma_f32_32x32x16_bf16 v[0:15], v[184:187], v[192:195], v[0:15]
	s_waitcnt lgkmcnt(4)
	v_mfma_f32_32x32x16_bf16 v[48:63], v[64:67], v[68:71], v[48:63]
	s_waitcnt lgkmcnt(1)
	v_mfma_f32_32x32x16_bf16 v[32:47], v[64:67], v[80:83], v[32:47]
	ds_read_b128 v[64:67], v128 offset:4608
	ds_read_b128 v[88:91], v128 offset:4640
	s_waitcnt lgkmcnt(1)
	v_mfma_f32_32x32x16_bf16 v[16:31], v[64:67], v[68:71], v[16:31]
	v_mfma_f32_32x32x16_bf16 v[0:15], v[64:67], v[80:83], v[0:15]
	v_mfma_f32_32x32x16_bf16 v[48:63], v[72:75], v[76:79], v[48:63]
	v_mfma_f32_32x32x16_bf16 v[32:47], v[72:75], v[84:87], v[32:47]
	ds_read_b128 v[64:67], v128 offset:64
	ds_read_b128 v[68:71], v129 offset:18496
	ds_read_b128 v[72:75], v128 offset:96
	ds_read_b128 v[92:95], v129 offset:18528
	s_waitcnt lgkmcnt(4)
	v_mfma_f32_32x32x16_bf16 v[16:31], v[88:91], v[76:79], v[16:31]
	ds_read_b128 v[76:79], v129 offset:23104
	ds_read_b128 v[136:139], v129 offset:23136
	v_mfma_f32_32x32x16_bf16 v[0:15], v[88:91], v[84:87], v[0:15]
	s_waitcnt lgkmcnt(4)
	v_mfma_f32_32x32x16_bf16 v[48:63], v[64:67], v[68:71], v[48:63]
	s_waitcnt lgkmcnt(1)
	v_mfma_f32_32x32x16_bf16 v[32:47], v[64:67], v[76:79], v[32:47]
	ds_read_b128 v[64:67], v128 offset:4672
	ds_read_b128 v[184:187], v128 offset:4704
	s_waitcnt lgkmcnt(1)
	v_mfma_f32_32x32x16_bf16 v[16:31], v[64:67], v[68:71], v[16:31]
	v_mfma_f32_32x32x16_bf16 v[0:15], v[64:67], v[76:79], v[0:15]
	v_mfma_f32_32x32x16_bf16 v[48:63], v[72:75], v[92:95], v[48:63]
	v_mfma_f32_32x32x16_bf16 v[32:47], v[72:75], v[136:139], v[32:47]
	global_load_dwordx4 v[80:83], v[196:197], off offset:2176
	global_load_dwordx4 v[64:67], v[198:199], off offset:2176
	global_load_dwordx4 v[68:71], v[200:201], off offset:2176
	global_load_dwordx4 v[72:75], v[202:203], off offset:2176
	global_load_dwordx4 v[76:79], v[204:205], off offset:2176
	global_load_dwordx4 v[84:87], v[206:207], off offset:2176
	global_load_dwordx4 v[88:91], v[208:209], off offset:2176
	s_waitcnt lgkmcnt(0)
	v_mfma_f32_32x32x16_bf16 v[16:31], v[184:187], v[92:95], v[16:31]
	global_load_dwordx4 v[92:95], v[210:211], off offset:2176
	v_mfma_f32_32x32x16_bf16 v[0:15], v[184:187], v[136:139], v[0:15]
	s_cbranch_scc1 .LBB0_883
	s_barrier
	s_setprio 2
	s_setprio 1
	s_waitcnt vmcnt(15)
	ds_write_b128 v134, v[96:99]
	s_waitcnt vmcnt(14)
	ds_write_b128 v134, v[100:103] offset:4608
	s_waitcnt vmcnt(13)
	ds_write_b128 v134, v[104:107] offset:9216
	s_waitcnt vmcnt(12)
	ds_write_b128 v134, v[108:111] offset:13824
	s_waitcnt vmcnt(11)
	ds_write_b128 v134, v[112:115] offset:18432
	s_waitcnt vmcnt(10)
	ds_write_b128 v134, v[116:119] offset:23040
	s_waitcnt vmcnt(9)
	ds_write_b128 v134, v[120:123] offset:27648
	s_waitcnt vmcnt(8)
	ds_write_b128 v134, v[124:127] offset:32256
	s_waitcnt lgkmcnt(0)
	s_barrier
	s_setprio 2
	ds_read_b128 v[96:99], v128 offset:4608
	ds_read_b128 v[100:103], v129 offset:23040
	ds_read_b128 v[104:107], v128
	ds_read_b128 v[108:111], v128 offset:32
	ds_read_b128 v[112:115], v129 offset:18432
	ds_read_b128 v[116:119], v129 offset:18464
	s_waitcnt lgkmcnt(1)
	v_mfma_f32_32x32x16_bf16 v[48:63], v[104:107], v[112:115], v[48:63]
	s_add_i32 s73, s73, 1
	s_addk_i32 s50, 0x800
	s_cmp_eq_u32 s73, 4
	v_mfma_f32_32x32x16_bf16 v[32:47], v[104:107], v[100:103], v[32:47]
	v_mfma_f32_32x32x16_bf16 v[16:31], v[96:99], v[112:115], v[16:31]
	v_mfma_f32_32x32x16_bf16 v[0:15], v[96:99], v[100:103], v[0:15]
	ds_read_b128 v[96:99], v128 offset:4640
	ds_read_b128 v[100:103], v129 offset:23072
	s_waitcnt lgkmcnt(2)
	v_mfma_f32_32x32x16_bf16 v[48:63], v[108:111], v[116:119], v[48:63]
	s_waitcnt lgkmcnt(0)
	v_mfma_f32_32x32x16_bf16 v[32:47], v[108:111], v[100:103], v[32:47]
	v_mfma_f32_32x32x16_bf16 v[16:31], v[96:99], v[116:119], v[16:31]
	v_mfma_f32_32x32x16_bf16 v[0:15], v[96:99], v[100:103], v[0:15]
	ds_read_b128 v[96:99], v128 offset:64
	ds_read_b128 v[100:103], v128 offset:4672
	ds_read_b128 v[104:107], v129 offset:18496
	ds_read_b128 v[108:111], v129 offset:23104
	s_waitcnt lgkmcnt(1)
	v_mfma_f32_32x32x16_bf16 v[48:63], v[96:99], v[104:107], v[48:63]
	s_waitcnt lgkmcnt(0)
	v_mfma_f32_32x32x16_bf16 v[32:47], v[96:99], v[108:111], v[32:47]
	v_mfma_f32_32x32x16_bf16 v[16:31], v[100:103], v[104:107], v[16:31]
	v_mfma_f32_32x32x16_bf16 v[0:15], v[100:103], v[108:111], v[0:15]
	ds_read_b128 v[96:99], v128 offset:96
	ds_read_b128 v[100:103], v128 offset:4704
	ds_read_b128 v[104:107], v129 offset:18528
	ds_read_b128 v[108:111], v129 offset:23136
	s_waitcnt lgkmcnt(0)
	s_barrier
; DI float sigmf(float x) { return __builtin_amdgcn_rcpf(1.f + __expf(-x)); }
; DI void gemm_128_2set(const bf16_t* __restrict__ A, int lda, const bf16_t* __restrict__ B, int ldb, int K, f32x16 (&acc)[2][2], bf16_t* sA, bf16_t* sB) {
;     ...
;   ST2(qa0, qa1, qa2, qa3, qb0, qb1, qb2, qb3)
;   __syncthreads();
;   MMA2()
; DI void phase_merge(CP p, const Ptrs& w, int l, bf16_t* sA, bf16_t* sB, unsigned* sU) {
;     ...
; #pragma unroll
;       for (int a = 0; a < 2; ++a)
; #pragma unroll
;         for (int c = 0; c < 2; ++c)
; #pragma unroll
;           for (int i = 0; i < 8; ++i) {
;             unsigned uv = sU[((a * 2 + c) * 8 + i) * 256 + tid];
;             float u0 = __uint_as_float(uv << 16), u1 = __uint_as_float(uv & 0xffff0000u);
;             const unsigned tv = totp[a][c][i];
;             float t0 = __uint_as_float(tv << 16) + sigmf(G[a][c][2 * i]) * u0;
;             float t1 = __uint_as_float(tv & 0xffff0000u) + sigmf(G[a][c][2 * i + 1]) * u1;
;             totp[a][c][i] = pack2(t0, t1);
;           }
	s_setprio 2
	s_setprio 1
	s_waitcnt vmcnt(7)
	ds_write_b128 v134, v[80:83]
	s_waitcnt vmcnt(6)
	ds_write_b128 v134, v[64:67] offset:4608
	s_waitcnt vmcnt(5)
	ds_write_b128 v134, v[68:71] offset:9216
	s_waitcnt vmcnt(4)
	ds_write_b128 v134, v[72:75] offset:13824
	s_waitcnt vmcnt(3)
	ds_write_b128 v134, v[76:79] offset:18432
	s_waitcnt vmcnt(2)
	ds_write_b128 v134, v[84:87] offset:23040
	s_waitcnt vmcnt(1)
	ds_write_b128 v134, v[88:91] offset:27648
	s_waitcnt vmcnt(0)
	ds_write_b128 v134, v[92:95] offset:32256
	s_waitcnt lgkmcnt(0)
	s_barrier
	s_setprio 2
	v_mfma_f32_32x32x16_bf16 v[48:63], v[96:99], v[104:107], v[48:63]
	ds_read_b128 v[64:67], v128 offset:4608
	ds_read_b128 v[68:71], v129 offset:23040
	ds_read_b128 v[72:75], v128
	ds_read_b128 v[76:79], v128 offset:32
	ds_read_b128 v[80:83], v129 offset:18432
	ds_read_b128 v[84:87], v129 offset:18464
	v_mfma_f32_32x32x16_bf16 v[32:47], v[96:99], v[108:111], v[32:47]
	v_mfma_f32_32x32x16_bf16 v[16:31], v[100:103], v[104:107], v[16:31]
	v_mfma_f32_32x32x16_bf16 v[0:15], v[100:103], v[108:111], v[0:15]
	s_waitcnt lgkmcnt(1)
	v_mfma_f32_32x32x16_bf16 v[48:63], v[72:75], v[80:83], v[48:63]
	v_mfma_f32_32x32x16_bf16 v[32:47], v[72:75], v[68:71], v[32:47]
	v_mfma_f32_32x32x16_bf16 v[16:31], v[64:67], v[80:83], v[16:31]
	v_mfma_f32_32x32x16_bf16 v[0:15], v[64:67], v[68:71], v[0:15]
	ds_read_b128 v[64:67], v128 offset:4640
	ds_read_b128 v[68:71], v129 offset:23072
	s_waitcnt lgkmcnt(2)
	v_mfma_f32_32x32x16_bf16 v[48:63], v[76:79], v[84:87], v[48:63]
	s_waitcnt lgkmcnt(0)
	v_mfma_f32_32x32x16_bf16 v[32:47], v[76:79], v[68:71], v[32:47]
	v_mfma_f32_32x32x16_bf16 v[16:31], v[64:67], v[84:87], v[16:31]
	v_mfma_f32_32x32x16_bf16 v[0:15], v[64:67], v[68:71], v[0:15]
	ds_read_b128 v[64:67], v128 offset:64
	ds_read_b128 v[68:71], v128 offset:4672
	ds_read_b128 v[72:75], v129 offset:18496
	ds_read_b128 v[76:79], v129 offset:23104
	s_waitcnt lgkmcnt(1)
	v_mfma_f32_32x32x16_bf16 v[48:63], v[64:67], v[72:75], v[48:63]
	s_waitcnt lgkmcnt(0)
	v_mfma_f32_32x32x16_bf16 v[32:47], v[64:67], v[76:79], v[32:47]
	v_mfma_f32_32x32x16_bf16 v[16:31], v[68:71], v[72:75], v[16:31]
	v_mfma_f32_32x32x16_bf16 v[0:15], v[68:71], v[76:79], v[0:15]
	ds_read_b128 v[64:67], v128 offset:96
	ds_read_b128 v[68:71], v128 offset:4704
	ds_read_b128 v[72:75], v129 offset:18528
	ds_read_b128 v[76:79], v129 offset:23136
	s_waitcnt lgkmcnt(1)
	v_mfma_f32_32x32x16_bf16 v[48:63], v[64:67], v[72:75], v[48:63]
	s_waitcnt lgkmcnt(0)
	v_mfma_f32_32x32x16_bf16 v[32:47], v[64:67], v[76:79], v[32:47]
	s_nop 9
	v_mul_f32_e32 v48, 0xbfb8aa3b, v48
	v_mul_f32_e32 v49, 0xbfb8aa3b, v49
	v_exp_f32_e32 v48, v48
	v_exp_f32_e32 v49, v49
	v_mul_f32_e32 v50, 0xbfb8aa3b, v50
	v_mul_f32_e32 v51, 0xbfb8aa3b, v51
	v_exp_f32_e32 v50, v50
	v_exp_f32_e32 v51, v51
	ds_read2st64_b32 v[64:65], v140 offset0:144 offset1:148
	v_add_f32_e32 v48, 1.0, v48
	v_add_f32_e32 v49, 1.0, v49
	v_rcp_f32_e32 v48, v48
	v_rcp_f32_e32 v49, v49
	v_add_f32_e32 v50, 1.0, v50
	v_add_f32_e32 v51, 1.0, v51
	v_rcp_f32_e32 v50, v50
	v_rcp_f32_e32 v51, v51
	v_mfma_f32_32x32x16_bf16 v[16:31], v[68:71], v[72:75], v[16:31]
	s_waitcnt lgkmcnt(0)
	v_lshlrev_b32_e32 v66, 16, v64
	v_and_b32_e32 v67, 0xffff0000, v64
	v_lshlrev_b32_e32 v64, 16, v182
	v_mul_f32_e32 v32, 0xbfb8aa3b, v32
	v_mul_f32_e32 v33, 0xbfb8aa3b, v33
	v_exp_f32_e32 v32, v32
	v_exp_f32_e32 v33, v33
	v_mfma_f32_32x32x16_bf16 v[0:15], v[68:71], v[76:79], v[0:15]
	s_setprio 0
	v_lshlrev_b32_e32 v68, 16, v183
	v_and_b32_e32 v69, 0xffff0000, v183
	v_fma_f32 v48, v48, v66, v68
	v_fma_f32 v49, v49, v67, v69
	v_mul_f32_e32 v34, 0xbfb8aa3b, v34
	v_cvt_pk_bf16_f32 v183, v48, v49
	v_lshlrev_b32_e32 v48, 16, v65
	v_and_b32_e32 v49, 0xffff0000, v65
	v_and_b32_e32 v65, 0xffff0000, v182
	v_pk_fma_f32 v[48:49], v[50:51], v[48:49], v[64:65]
	v_lshlrev_b32_e32 v64, 16, v181
	v_cvt_pk_bf16_f32 v182, v48, v49
	ds_read2st64_b32 v[48:49], v140 offset0:152 offset1:156
	v_and_b32_e32 v65, 0xffff0000, v181
	v_mul_f32_e32 v35, 0xbfb8aa3b, v35
	v_exp_f32_e32 v34, v34
	v_exp_f32_e32 v35, v35
	s_waitcnt lgkmcnt(0)
	v_lshlrev_b32_e32 v50, 16, v48
	v_and_b32_e32 v51, 0xffff0000, v48
	v_mul_f32_e32 v48, 0xbfb8aa3b, v52
	v_exp_f32_e32 v48, v48
	v_add_f32_e32 v32, 1.0, v32
	v_add_f32_e32 v33, 1.0, v33
	v_rcp_f32_e32 v32, v32
	v_add_f32_e32 v48, 1.0, v48
	v_rcp_f32_e32 v52, v48
	v_mul_f32_e32 v48, 0xbfb8aa3b, v53
	v_exp_f32_e32 v48, v48
	v_rcp_f32_e32 v33, v33
	v_add_f32_e32 v34, 1.0, v34
	v_add_f32_e32 v35, 1.0, v35
	v_add_f32_e32 v48, 1.0, v48
	v_rcp_f32_e32 v53, v48
	v_lshlrev_b32_e32 v48, 16, v49
	v_and_b32_e32 v49, 0xffff0000, v49
	v_rcp_f32_e32 v34, v34
	v_pk_fma_f32 v[50:51], v[52:53], v[50:51], v[64:65]
	v_mul_f32_e32 v53, 0xbfb8aa3b, v55
	v_cvt_pk_bf16_f32 v181, v50, v51
	v_mul_f32_e32 v51, 0xbfb8aa3b, v54
	v_exp_f32_e32 v51, v51
	v_exp_f32_e32 v53, v53
	v_lshlrev_b32_e32 v50, 16, v180
	v_rcp_f32_e32 v35, v35
	v_add_f32_e32 v51, 1.0, v51
	v_add_f32_e32 v53, 1.0, v53
	v_rcp_f32_e32 v52, v51
	v_rcp_f32_e32 v53, v53
	v_and_b32_e32 v51, 0xffff0000, v180
	v_mul_f32_e32 v16, 0xbfb8aa3b, v16
	v_mul_f32_e32 v17, 0xbfb8aa3b, v17
	v_pk_fma_f32 v[48:49], v[52:53], v[48:49], v[50:51]
	v_lshlrev_b32_e32 v52, 16, v179
	v_cvt_pk_bf16_f32 v180, v48, v49
	ds_read2st64_b32 v[48:49], v140 offset0:160 offset1:164
	v_and_b32_e32 v53, 0xffff0000, v179
	v_exp_f32_e32 v16, v16
	v_exp_f32_e32 v17, v17
	v_mul_f32_e32 v18, 0xbfb8aa3b, v18
	s_waitcnt lgkmcnt(0)
; DI float sigmf(float x) { return __builtin_amdgcn_rcpf(1.f + __expf(-x)); }
; DI void phase_merge(CP p, const Ptrs& w, int l, bf16_t* sA, bf16_t* sB, unsigned* sU) {
;     ...
; #pragma unroll
;       for (int a = 0; a < 2; ++a)
; #pragma unroll
;         for (int c = 0; c < 2; ++c)
; #pragma unroll
;           for (int i = 0; i < 8; ++i) {
;             unsigned uv = sU[((a * 2 + c) * 8 + i) * 256 + tid];
;             float u0 = __uint_as_float(uv << 16), u1 = __uint_as_float(uv & 0xffff0000u);
;             const unsigned tv = totp[a][c][i];
;             float t0 = __uint_as_float(tv << 16) + sigmf(G[a][c][2 * i]) * u0;
;             float t1 = __uint_as_float(tv & 0xffff0000u) + sigmf(G[a][c][2 * i + 1]) * u1;
;             totp[a][c][i] = pack2(t0, t1);
;           }
	v_lshlrev_b32_e32 v50, 16, v48
	v_and_b32_e32 v51, 0xffff0000, v48
	v_mul_f32_e32 v48, 0xbfb8aa3b, v56
	v_exp_f32_e32 v48, v48
	v_mul_f32_e32 v19, 0xbfb8aa3b, v19
	v_exp_f32_e32 v18, v18
	v_exp_f32_e32 v19, v19
	v_add_f32_e32 v48, 1.0, v48
	v_rcp_f32_e32 v54, v48
	v_mul_f32_e32 v48, 0xbfb8aa3b, v57
	v_exp_f32_e32 v48, v48
	v_add_f32_e32 v16, 1.0, v16
	v_add_f32_e32 v17, 1.0, v17
	v_rcp_f32_e32 v16, v16
	v_add_f32_e32 v48, 1.0, v48
	v_rcp_f32_e32 v55, v48
	v_lshlrev_b32_e32 v48, 16, v49
	v_and_b32_e32 v49, 0xffff0000, v49
	v_rcp_f32_e32 v17, v17
	v_pk_fma_f32 v[50:51], v[54:55], v[50:51], v[52:53]
	v_mul_f32_e32 v53, 0xbfb8aa3b, v59
	v_cvt_pk_bf16_f32 v179, v50, v51
	v_mul_f32_e32 v51, 0xbfb8aa3b, v58
	v_exp_f32_e32 v51, v51
	v_exp_f32_e32 v53, v53
	v_lshlrev_b32_e32 v50, 16, v177
	v_add_f32_e32 v18, 1.0, v18
	v_add_f32_e32 v51, 1.0, v51
	v_add_f32_e32 v53, 1.0, v53
	v_rcp_f32_e32 v52, v51
	v_rcp_f32_e32 v53, v53
	v_and_b32_e32 v51, 0xffff0000, v177
	v_add_f32_e32 v19, 1.0, v19
	v_rcp_f32_e32 v18, v18
	v_pk_fma_f32 v[48:49], v[52:53], v[48:49], v[50:51]
	v_lshlrev_b32_e32 v52, 16, v178
	v_cvt_pk_bf16_f32 v177, v48, v49
	ds_read2st64_b32 v[48:49], v140 offset0:168 offset1:172
	v_and_b32_e32 v53, 0xffff0000, v178
	v_rcp_f32_e32 v19, v19
	v_mul_f32_e32 v0, 0xbfb8aa3b, v0
	v_mul_f32_e32 v1, 0xbfb8aa3b, v1
	s_waitcnt lgkmcnt(0)
	v_lshlrev_b32_e32 v50, 16, v48
	v_and_b32_e32 v51, 0xffff0000, v48
	v_mul_f32_e32 v48, 0xbfb8aa3b, v60
	v_exp_f32_e32 v48, v48
	v_exp_f32_e32 v0, v0
	v_exp_f32_e32 v1, v1
	v_mul_f32_e32 v2, 0xbfb8aa3b, v2
	v_add_f32_e32 v48, 1.0, v48
	v_rcp_f32_e32 v54, v48
	v_mul_f32_e32 v48, 0xbfb8aa3b, v61
	v_exp_f32_e32 v48, v48
	v_mul_f32_e32 v3, 0xbfb8aa3b, v3
	v_exp_f32_e32 v2, v2
	v_exp_f32_e32 v3, v3
	v_add_f32_e32 v48, 1.0, v48
	v_rcp_f32_e32 v55, v48
	v_lshlrev_b32_e32 v48, 16, v49
	v_and_b32_e32 v49, 0xffff0000, v49
	v_add_f32_e32 v0, 1.0, v0
	v_pk_fma_f32 v[50:51], v[54:55], v[50:51], v[52:53]
	v_mul_f32_e32 v53, 0xbfb8aa3b, v63
	v_cvt_pk_bf16_f32 v178, v50, v51
	v_mul_f32_e32 v51, 0xbfb8aa3b, v62
	v_exp_f32_e32 v51, v51
	v_exp_f32_e32 v53, v53
	v_lshlrev_b32_e32 v50, 16, v173
	v_add_f32_e32 v1, 1.0, v1
	v_add_f32_e32 v51, 1.0, v51
	v_add_f32_e32 v53, 1.0, v53
	v_rcp_f32_e32 v52, v51
	v_rcp_f32_e32 v53, v53
	v_and_b32_e32 v51, 0xffff0000, v173
	v_rcp_f32_e32 v0, v0
	v_rcp_f32_e32 v1, v1
	v_pk_fma_f32 v[48:49], v[52:53], v[48:49], v[50:51]
	v_lshlrev_b32_e32 v52, 16, v176
	v_cvt_pk_bf16_f32 v173, v48, v49
	ds_read2st64_b32 v[48:49], v140 offset0:176 offset1:180
	v_and_b32_e32 v53, 0xffff0000, v176
	v_add_f32_e32 v2, 1.0, v2
	v_add_f32_e32 v3, 1.0, v3
	v_rcp_f32_e32 v2, v2
	s_waitcnt lgkmcnt(0)
	v_lshlrev_b32_e32 v50, 16, v48
	v_and_b32_e32 v51, 0xffff0000, v48
	v_pk_fma_f32 v[32:33], v[32:33], v[50:51], v[52:53]
	v_lshlrev_b32_e32 v48, 16, v170
	v_cvt_pk_bf16_f32 v176, v32, v33
	v_lshlrev_b32_e32 v32, 16, v49
	v_and_b32_e32 v33, 0xffff0000, v49
	v_and_b32_e32 v49, 0xffff0000, v170
	v_pk_fma_f32 v[32:33], v[34:35], v[32:33], v[48:49]
	v_lshlrev_b32_e32 v48, 16, v175
	v_cvt_pk_bf16_f32 v170, v32, v33
	ds_read2st64_b32 v[32:33], v140 offset0:184 offset1:188
	v_and_b32_e32 v49, 0xffff0000, v175
	v_rcp_f32_e32 v3, v3
	s_waitcnt lgkmcnt(0)
	v_lshlrev_b32_e32 v34, 16, v32
	v_and_b32_e32 v35, 0xffff0000, v32
	v_mul_f32_e32 v32, 0xbfb8aa3b, v36
	v_exp_f32_e32 v32, v32
	s_nop 0
	v_add_f32_e32 v32, 1.0, v32
	v_rcp_f32_e32 v36, v32
	v_mul_f32_e32 v32, 0xbfb8aa3b, v37
	v_exp_f32_e32 v32, v32
	s_nop 0
	v_add_f32_e32 v32, 1.0, v32
	v_rcp_f32_e32 v37, v32
	v_lshlrev_b32_e32 v32, 16, v33
	v_and_b32_e32 v33, 0xffff0000, v33
	v_pk_fma_f32 v[34:35], v[36:37], v[34:35], v[48:49]
	s_nop 0
	v_cvt_pk_bf16_f32 v175, v34, v35
	v_mul_f32_e32 v35, 0xbfb8aa3b, v38
	v_mul_f32_e32 v37, 0xbfb8aa3b, v39
	v_exp_f32_e32 v35, v35
	v_exp_f32_e32 v37, v37
	v_lshlrev_b32_e32 v34, 16, v174
	v_add_f32_e32 v35, 1.0, v35
	v_add_f32_e32 v37, 1.0, v37
	v_rcp_f32_e32 v36, v35
	v_rcp_f32_e32 v37, v37
	v_and_b32_e32 v35, 0xffff0000, v174
	v_pk_fma_f32 v[32:33], v[36:37], v[32:33], v[34:35]
	s_nop 0
	v_cvt_pk_bf16_f32 v174, v32, v33
	ds_read2st64_b32 v[32:33], v140 offset0:192 offset1:196
	v_lshlrev_b32_e32 v36, 16, v172
	v_and_b32_e32 v37, 0xffff0000, v172
	s_waitcnt lgkmcnt(0)
	v_lshlrev_b32_e32 v34, 16, v32
	v_and_b32_e32 v35, 0xffff0000, v32
	v_mul_f32_e32 v32, 0xbfb8aa3b, v40
	v_exp_f32_e32 v32, v32
	s_nop 0
	v_add_f32_e32 v32, 1.0, v32
	v_rcp_f32_e32 v38, v32
	v_mul_f32_e32 v32, 0xbfb8aa3b, v41
	v_exp_f32_e32 v32, v32
	s_nop 0
	v_add_f32_e32 v32, 1.0, v32
	v_rcp_f32_e32 v39, v32
	v_lshlrev_b32_e32 v32, 16, v33
	v_and_b32_e32 v33, 0xffff0000, v33
	v_pk_fma_f32 v[34:35], v[38:39], v[34:35], v[36:37]
	s_nop 0
	v_cvt_pk_bf16_f32 v172, v34, v35
	v_mul_f32_e32 v35, 0xbfb8aa3b, v42
	v_mul_f32_e32 v37, 0xbfb8aa3b, v43
	v_exp_f32_e32 v35, v35
	v_exp_f32_e32 v37, v37
	v_lshlrev_b32_e32 v34, 16, v171
	v_add_f32_e32 v35, 1.0, v35
	v_add_f32_e32 v37, 1.0, v37
	v_rcp_f32_e32 v36, v35
	v_rcp_f32_e32 v37, v37
	v_and_b32_e32 v35, 0xffff0000, v171
	v_pk_fma_f32 v[32:33], v[36:37], v[32:33], v[34:35]
	s_nop 0
	v_cvt_pk_bf16_f32 v171, v32, v33
	ds_read2st64_b32 v[32:33], v140 offset0:200 offset1:204
	v_lshlrev_b32_e32 v36, 16, v169
	v_and_b32_e32 v37, 0xffff0000, v169
	s_waitcnt lgkmcnt(0)
; DI float sigmf(float x) { return __builtin_amdgcn_rcpf(1.f + __expf(-x)); }
; DI void phase_merge(CP p, const Ptrs& w, int l, bf16_t* sA, bf16_t* sB, unsigned* sU) {
;     ...
; #pragma unroll
;       for (int a = 0; a < 2; ++a)
; #pragma unroll
;         for (int c = 0; c < 2; ++c)
; #pragma unroll
;           for (int i = 0; i < 8; ++i) {
;             unsigned uv = sU[((a * 2 + c) * 8 + i) * 256 + tid];
;             float u0 = __uint_as_float(uv << 16), u1 = __uint_as_float(uv & 0xffff0000u);
;             const unsigned tv = totp[a][c][i];
;             float t0 = __uint_as_float(tv << 16) + sigmf(G[a][c][2 * i]) * u0;
;             float t1 = __uint_as_float(tv & 0xffff0000u) + sigmf(G[a][c][2 * i + 1]) * u1;
;             totp[a][c][i] = pack2(t0, t1);
;           }
	v_lshlrev_b32_e32 v34, 16, v32
	v_and_b32_e32 v35, 0xffff0000, v32
	v_mul_f32_e32 v32, 0xbfb8aa3b, v44
	v_exp_f32_e32 v32, v32
	s_nop 0
	v_add_f32_e32 v32, 1.0, v32
	v_rcp_f32_e32 v38, v32
	v_mul_f32_e32 v32, 0xbfb8aa3b, v45
	v_exp_f32_e32 v32, v32
	s_nop 0
	v_add_f32_e32 v32, 1.0, v32
	v_rcp_f32_e32 v39, v32
	v_lshlrev_b32_e32 v32, 16, v33
	v_and_b32_e32 v33, 0xffff0000, v33
	v_pk_fma_f32 v[34:35], v[38:39], v[34:35], v[36:37]
	s_nop 0
	v_cvt_pk_bf16_f32 v169, v34, v35
	v_mul_f32_e32 v35, 0xbfb8aa3b, v46
	v_mul_f32_e32 v37, 0xbfb8aa3b, v47
	v_exp_f32_e32 v35, v35
	v_exp_f32_e32 v37, v37
	v_lshlrev_b32_e32 v34, 16, v168
	v_add_f32_e32 v35, 1.0, v35
	v_add_f32_e32 v37, 1.0, v37
	v_rcp_f32_e32 v36, v35
	v_rcp_f32_e32 v37, v37
	v_and_b32_e32 v35, 0xffff0000, v168
	v_pk_fma_f32 v[32:33], v[36:37], v[32:33], v[34:35]
	s_nop 0
	v_cvt_pk_bf16_f32 v168, v32, v33
	ds_read2st64_b32 v[32:33], v140 offset0:208 offset1:212
	v_lshlrev_b32_e32 v36, 16, v167
	v_and_b32_e32 v37, 0xffff0000, v167
	s_waitcnt lgkmcnt(0)
	v_lshlrev_b32_e32 v34, 16, v32
	v_and_b32_e32 v35, 0xffff0000, v32
	v_pk_fma_f32 v[16:17], v[16:17], v[34:35], v[36:37]
	v_lshlrev_b32_e32 v32, 16, v164
	v_cvt_pk_bf16_f32 v167, v16, v17
	v_lshlrev_b32_e32 v16, 16, v33
	v_and_b32_e32 v17, 0xffff0000, v33
	v_and_b32_e32 v33, 0xffff0000, v164
	v_pk_fma_f32 v[16:17], v[18:19], v[16:17], v[32:33]
	v_lshlrev_b32_e32 v32, 16, v163
	v_cvt_pk_bf16_f32 v164, v16, v17
	ds_read2st64_b32 v[16:17], v140 offset0:216 offset1:220
	v_and_b32_e32 v33, 0xffff0000, v163
	s_waitcnt lgkmcnt(0)
	v_lshlrev_b32_e32 v18, 16, v16
	v_and_b32_e32 v19, 0xffff0000, v16
	v_mul_f32_e32 v16, 0xbfb8aa3b, v20
	v_exp_f32_e32 v16, v16
	s_nop 0
	v_add_f32_e32 v16, 1.0, v16
	v_rcp_f32_e32 v20, v16
	v_mul_f32_e32 v16, 0xbfb8aa3b, v21
	v_exp_f32_e32 v16, v16
	s_nop 0
	v_add_f32_e32 v16, 1.0, v16
	v_rcp_f32_e32 v21, v16
	v_lshlrev_b32_e32 v16, 16, v17
	v_and_b32_e32 v17, 0xffff0000, v17
	v_pk_fma_f32 v[18:19], v[20:21], v[18:19], v[32:33]
	s_nop 0
	v_cvt_pk_bf16_f32 v163, v18, v19
	v_mul_f32_e32 v19, 0xbfb8aa3b, v22
	v_mul_f32_e32 v21, 0xbfb8aa3b, v23
	v_exp_f32_e32 v19, v19
	v_exp_f32_e32 v21, v21
	v_lshlrev_b32_e32 v18, 16, v161
	v_add_f32_e32 v19, 1.0, v19
	v_add_f32_e32 v21, 1.0, v21
	v_rcp_f32_e32 v20, v19
	v_rcp_f32_e32 v21, v21
	v_and_b32_e32 v19, 0xffff0000, v161
	v_pk_fma_f32 v[16:17], v[20:21], v[16:17], v[18:19]
	s_nop 0
	v_cvt_pk_bf16_f32 v161, v16, v17
	ds_read2st64_b32 v[16:17], v140 offset0:224 offset1:228
	v_lshlrev_b32_e32 v20, 16, v155
	v_and_b32_e32 v21, 0xffff0000, v155
	s_waitcnt lgkmcnt(0)
	v_lshlrev_b32_e32 v18, 16, v16
	v_and_b32_e32 v19, 0xffff0000, v16
	v_mul_f32_e32 v16, 0xbfb8aa3b, v24
	v_exp_f32_e32 v16, v16
	s_nop 0
	v_add_f32_e32 v16, 1.0, v16
	v_rcp_f32_e32 v22, v16
	v_mul_f32_e32 v16, 0xbfb8aa3b, v25
	v_exp_f32_e32 v16, v16
	s_nop 0
	v_add_f32_e32 v16, 1.0, v16
	v_rcp_f32_e32 v23, v16
	v_lshlrev_b32_e32 v16, 16, v17
	v_and_b32_e32 v17, 0xffff0000, v17
	v_pk_fma_f32 v[18:19], v[22:23], v[18:19], v[20:21]
	s_nop 0
	v_cvt_pk_bf16_f32 v155, v18, v19
	v_mul_f32_e32 v19, 0xbfb8aa3b, v26
	v_mul_f32_e32 v21, 0xbfb8aa3b, v27
	v_exp_f32_e32 v19, v19
	v_exp_f32_e32 v21, v21
	v_lshlrev_b32_e32 v18, 16, v154
	v_add_f32_e32 v19, 1.0, v19
	v_add_f32_e32 v21, 1.0, v21
	v_rcp_f32_e32 v20, v19
	v_rcp_f32_e32 v21, v21
	v_and_b32_e32 v19, 0xffff0000, v154
	v_pk_fma_f32 v[16:17], v[20:21], v[16:17], v[18:19]
	s_nop 0
	v_cvt_pk_bf16_f32 v154, v16, v17
	ds_read2st64_b32 v[16:17], v140 offset0:232 offset1:236
	v_lshlrev_b32_e32 v20, 16, v153
	v_and_b32_e32 v21, 0xffff0000, v153
	s_waitcnt lgkmcnt(0)
	v_lshlrev_b32_e32 v18, 16, v16
	v_and_b32_e32 v19, 0xffff0000, v16
	v_mul_f32_e32 v16, 0xbfb8aa3b, v28
	v_exp_f32_e32 v16, v16
	s_nop 0
	v_add_f32_e32 v16, 1.0, v16
	v_rcp_f32_e32 v22, v16
	v_mul_f32_e32 v16, 0xbfb8aa3b, v29
	v_exp_f32_e32 v16, v16
	s_nop 0
	v_add_f32_e32 v16, 1.0, v16
	v_rcp_f32_e32 v23, v16
	v_lshlrev_b32_e32 v16, 16, v17
	v_and_b32_e32 v17, 0xffff0000, v17
	v_pk_fma_f32 v[18:19], v[22:23], v[18:19], v[20:21]
	s_nop 0
	v_cvt_pk_bf16_f32 v153, v18, v19
	v_mul_f32_e32 v19, 0xbfb8aa3b, v30
	v_mul_f32_e32 v21, 0xbfb8aa3b, v31
	v_exp_f32_e32 v19, v19
	v_exp_f32_e32 v21, v21
	v_lshlrev_b32_e32 v18, 16, v152
	v_add_f32_e32 v19, 1.0, v19
	v_add_f32_e32 v21, 1.0, v21
	v_rcp_f32_e32 v20, v19
	v_rcp_f32_e32 v21, v21
	v_and_b32_e32 v19, 0xffff0000, v152
	v_pk_fma_f32 v[16:17], v[20:21], v[16:17], v[18:19]
	s_nop 0
	v_cvt_pk_bf16_f32 v152, v16, v17
	ds_read2st64_b32 v[16:17], v140 offset0:240 offset1:244
	v_lshlrev_b32_e32 v20, 16, v151
	v_and_b32_e32 v21, 0xffff0000, v151
	s_waitcnt lgkmcnt(0)
	v_lshlrev_b32_e32 v18, 16, v16
	v_and_b32_e32 v19, 0xffff0000, v16
	v_pk_fma_f32 v[0:1], v[0:1], v[18:19], v[20:21]
	v_lshlrev_b32_e32 v16, 16, v150
	v_cvt_pk_bf16_f32 v151, v0, v1
	v_lshlrev_b32_e32 v0, 16, v17
	v_and_b32_e32 v1, 0xffff0000, v17
	v_and_b32_e32 v17, 0xffff0000, v150
	v_pk_fma_f32 v[0:1], v[2:3], v[0:1], v[16:17]
	v_lshlrev_b32_e32 v16, 16, v149
	v_cvt_pk_bf16_f32 v150, v0, v1
	ds_read2st64_b32 v[0:1], v140 offset0:248 offset1:252
	v_and_b32_e32 v17, 0xffff0000, v149
	s_waitcnt lgkmcnt(0)
	v_lshlrev_b32_e32 v2, 16, v0
	v_and_b32_e32 v3, 0xffff0000, v0
	v_mul_f32_e32 v0, 0xbfb8aa3b, v4
	v_exp_f32_e32 v0, v0
	s_nop 0
	v_add_f32_e32 v0, 1.0, v0
	v_rcp_f32_e32 v4, v0
	v_mul_f32_e32 v0, 0xbfb8aa3b, v5
	v_exp_f32_e32 v0, v0
	s_nop 0
	v_add_f32_e32 v0, 1.0, v0
	v_rcp_f32_e32 v5, v0
	v_lshlrev_b32_e32 v0, 16, v1
	v_and_b32_e32 v1, 0xffff0000, v1
	v_pk_fma_f32 v[2:3], v[4:5], v[2:3], v[16:17]
	s_nop 0
	v_cvt_pk_bf16_f32 v149, v2, v3
	v_mul_f32_e32 v3, 0xbfb8aa3b, v6
	v_mul_f32_e32 v5, 0xbfb8aa3b, v7
	v_exp_f32_e32 v3, v3
	v_exp_f32_e32 v5, v5
	v_lshlrev_b32_e32 v2, 16, v148
	v_add_f32_e32 v3, 1.0, v3
	v_add_f32_e32 v5, 1.0, v5
	v_rcp_f32_e32 v4, v3
	v_rcp_f32_e32 v5, v5
	v_and_b32_e32 v3, 0xffff0000, v148
	v_pk_fma_f32 v[0:1], v[4:5], v[0:1], v[2:3]
	s_nop 0
	v_cvt_pk_bf16_f32 v148, v0, v1
	ds_read2st64_b32 v[0:1], v141 offset0:112 offset1:116
	v_lshlrev_b32_e32 v4, 16, v147
	v_and_b32_e32 v5, 0xffff0000, v147
	s_waitcnt lgkmcnt(0)
; DI float sigmf(float x) { return __builtin_amdgcn_rcpf(1.f + __expf(-x)); }
; DI int crow(int i, int h) { return (i & 3) + 8 * (i >> 2) + 4 * h; }
; DI void phase_merge(CP p, const Ptrs& w, int l, bf16_t* sA, bf16_t* sB, unsigned* sU) {
;     ...
; #pragma unroll
;       for (int a = 0; a < 2; ++a)
; #pragma unroll
;         for (int c = 0; c < 2; ++c)
; #pragma unroll
;           for (int i = 0; i < 8; ++i) {
;             unsigned uv = sU[((a * 2 + c) * 8 + i) * 256 + tid];
;             float u0 = __uint_as_float(uv << 16), u1 = __uint_as_float(uv & 0xffff0000u);
;             const unsigned tv = totp[a][c][i];
;             float t0 = __uint_as_float(tv << 16) + sigmf(G[a][c][2 * i]) * u0;
;             float t1 = __uint_as_float(tv & 0xffff0000u) + sigmf(G[a][c][2 * i + 1]) * u1;
;             totp[a][c][i] = pack2(t0, t1);
;           }
;     }
;     bf16_t* dst = w.R2;
; #pragma unroll
;     for (int mi = 0; mi < 2; ++mi)
; #pragma unroll
;       for (int ni = 0; ni < 2; ++ni)
; #pragma unroll
;         for (int i = 0; i < 16; ++i) {
;           int row = m0 + wm * 64 + mi * 32 + crow(i, h), col = n0 + wn * 64 + ni * 32 + r;
;           const unsigned tv = totp[mi][ni][i >> 1];
;           dst[(size_t)row * 2048 + col] = (bf16_t)((i & 1) ? (tv >> 16) : (tv & 0xffffu));
	v_lshlrev_b32_e32 v2, 16, v0
	v_and_b32_e32 v3, 0xffff0000, v0
	v_mul_f32_e32 v0, 0xbfb8aa3b, v8
	v_exp_f32_e32 v0, v0
	s_nop 0
	v_add_f32_e32 v0, 1.0, v0
	v_rcp_f32_e32 v6, v0
	v_mul_f32_e32 v0, 0xbfb8aa3b, v9
	v_exp_f32_e32 v0, v0
	s_nop 0
	v_add_f32_e32 v0, 1.0, v0
	v_rcp_f32_e32 v7, v0
	v_lshlrev_b32_e32 v0, 16, v1
	v_and_b32_e32 v1, 0xffff0000, v1
	v_pk_fma_f32 v[2:3], v[6:7], v[2:3], v[4:5]
	s_nop 0
	v_cvt_pk_bf16_f32 v147, v2, v3
	v_mul_f32_e32 v3, 0xbfb8aa3b, v10
	v_mul_f32_e32 v5, 0xbfb8aa3b, v11
	v_exp_f32_e32 v3, v3
	v_exp_f32_e32 v5, v5
	v_lshlrev_b32_e32 v2, 16, v146
	v_add_f32_e32 v3, 1.0, v3
	v_add_f32_e32 v5, 1.0, v5
	v_rcp_f32_e32 v4, v3
	v_rcp_f32_e32 v5, v5
	v_and_b32_e32 v3, 0xffff0000, v146
	v_pk_fma_f32 v[0:1], v[4:5], v[0:1], v[2:3]
	s_nop 0
	v_cvt_pk_bf16_f32 v146, v0, v1
	ds_read2st64_b32 v[0:1], v141 offset0:120 offset1:124
	v_lshlrev_b32_e32 v4, 16, v145
	v_and_b32_e32 v5, 0xffff0000, v145
	s_waitcnt lgkmcnt(0)
	v_lshlrev_b32_e32 v2, 16, v0
	v_and_b32_e32 v3, 0xffff0000, v0
	v_mul_f32_e32 v0, 0xbfb8aa3b, v12
	v_exp_f32_e32 v0, v0
	s_nop 0
	v_add_f32_e32 v0, 1.0, v0
	v_rcp_f32_e32 v6, v0
	v_mul_f32_e32 v0, 0xbfb8aa3b, v13
	v_exp_f32_e32 v0, v0
	s_nop 0
	v_add_f32_e32 v0, 1.0, v0
	v_rcp_f32_e32 v7, v0
	v_lshlrev_b32_e32 v0, 16, v1
	v_and_b32_e32 v1, 0xffff0000, v1
	v_pk_fma_f32 v[2:3], v[6:7], v[2:3], v[4:5]
	s_nop 0
	v_cvt_pk_bf16_f32 v145, v2, v3
	v_mul_f32_e32 v3, 0xbfb8aa3b, v14
	v_mul_f32_e32 v5, 0xbfb8aa3b, v15
	v_exp_f32_e32 v3, v3
	v_exp_f32_e32 v5, v5
	v_lshlrev_b32_e32 v2, 16, v144
	v_add_f32_e32 v3, 1.0, v3
	v_add_f32_e32 v5, 1.0, v5
	v_rcp_f32_e32 v4, v3
	v_rcp_f32_e32 v5, v5
	v_and_b32_e32 v3, 0xffff0000, v144
	v_pk_fma_f32 v[0:1], v[4:5], v[0:1], v[2:3]
	s_nop 0
	v_cvt_pk_bf16_f32 v144, v0, v1
	s_cbranch_scc0 .LBB0_871
	v_add_u32_e32 v0, s38, v142
	v_or_b32_e32 v2, s72, v143
	v_or_b32_e32 v6, 1, v0
	v_or_b32_e32 v8, 2, v0
	v_or_b32_e32 v10, 3, v0
	v_or_b32_e32 v12, 8, v0
	v_or_b32_e32 v14, 9, v0
	v_or_b32_e32 v16, 10, v0
	v_or_b32_e32 v18, 11, v0
	v_or_b32_e32 v20, 16, v0
	v_or_b32_e32 v22, 17, v0
	v_or_b32_e32 v24, 18, v0
	v_or_b32_e32 v26, 19, v0
	v_or_b32_e32 v28, 24, v0
	v_or_b32_e32 v30, 25, v0
	v_or_b32_e32 v32, 26, v0
	v_or_b32_e32 v34, 27, v0
	v_ashrrev_i32_e32 v3, 31, v2
	v_ashrrev_i32_e32 v1, 31, v0
	v_ashrrev_i32_e32 v7, 31, v6
	v_ashrrev_i32_e32 v9, 31, v8
	v_ashrrev_i32_e32 v11, 31, v10
	v_ashrrev_i32_e32 v13, 31, v12
	v_ashrrev_i32_e32 v15, 31, v14
	v_ashrrev_i32_e32 v17, 31, v16
	v_ashrrev_i32_e32 v19, 31, v18
	v_ashrrev_i32_e32 v21, 31, v20
	v_ashrrev_i32_e32 v23, 31, v22
	v_ashrrev_i32_e32 v25, 31, v24
	v_ashrrev_i32_e32 v27, 31, v26
	v_ashrrev_i32_e32 v29, 31, v28
	v_ashrrev_i32_e32 v31, 31, v30
	v_ashrrev_i32_e32 v33, 31, v32
	v_ashrrev_i32_e32 v35, 31, v34
	v_lshl_add_u64 v[2:3], v[2:3], 1, s[10:11]
	v_lshlrev_b64 v[4:5], 12, v[0:1]
	v_lshlrev_b64 v[6:7], 12, v[6:7]
	v_lshlrev_b64 v[8:9], 12, v[8:9]
	v_lshlrev_b64 v[10:11], 12, v[10:11]
	v_lshlrev_b64 v[12:13], 12, v[12:13]
	v_lshlrev_b64 v[14:15], 12, v[14:15]
	v_lshlrev_b64 v[16:17], 12, v[16:17]
	v_lshlrev_b64 v[18:19], 12, v[18:19]
	v_lshlrev_b64 v[20:21], 12, v[20:21]
	v_lshlrev_b64 v[22:23], 12, v[22:23]
	v_lshlrev_b64 v[24:25], 12, v[24:25]
	v_lshlrev_b64 v[26:27], 12, v[26:27]
	v_lshlrev_b64 v[28:29], 12, v[28:29]
	v_lshlrev_b64 v[30:31], 12, v[30:31]
	v_lshlrev_b64 v[32:33], 12, v[32:33]
	v_lshlrev_b64 v[34:35], 12, v[34:35]
	v_lshl_add_u64 v[4:5], v[2:3], 0, v[4:5]
	v_lshl_add_u64 v[6:7], v[2:3], 0, v[6:7]
	v_lshl_add_u64 v[8:9], v[2:3], 0, v[8:9]
	v_lshl_add_u64 v[10:11], v[2:3], 0, v[10:11]
	v_lshl_add_u64 v[12:13], v[2:3], 0, v[12:13]
	v_lshl_add_u64 v[14:15], v[2:3], 0, v[14:15]
	v_lshl_add_u64 v[16:17], v[2:3], 0, v[16:17]
	v_lshl_add_u64 v[18:19], v[2:3], 0, v[18:19]
	v_lshl_add_u64 v[20:21], v[2:3], 0, v[20:21]
	v_lshl_add_u64 v[22:23], v[2:3], 0, v[22:23]
	v_lshl_add_u64 v[24:25], v[2:3], 0, v[24:25]
	v_lshl_add_u64 v[26:27], v[2:3], 0, v[26:27]
	v_lshl_add_u64 v[28:29], v[2:3], 0, v[28:29]
	v_lshl_add_u64 v[30:31], v[2:3], 0, v[30:31]
	v_lshl_add_u64 v[32:33], v[2:3], 0, v[32:33]
	v_lshl_add_u64 v[34:35], v[2:3], 0, v[34:35]
	global_store_short v[4:5], v183, off
	global_store_short_d16_hi v[6:7], v183, off
	global_store_short v[8:9], v182, off
	global_store_short_d16_hi v[10:11], v182, off
	global_store_short v[12:13], v181, off
	global_store_short_d16_hi v[14:15], v181, off
	global_store_short v[16:17], v180, off
	global_store_short_d16_hi v[18:19], v180, off
	global_store_short v[20:21], v179, off
	global_store_short_d16_hi v[22:23], v179, off
	global_store_short v[24:25], v177, off
	global_store_short_d16_hi v[26:27], v177, off
	global_store_short v[28:29], v178, off
	global_store_short_d16_hi v[30:31], v178, off
	global_store_short v[32:33], v173, off
; DI int crow(int i, int h) { return (i & 3) + 8 * (i >> 2) + 4 * h; }
; DI void phase_merge(CP p, const Ptrs& w, int l, bf16_t* sA, bf16_t* sB, unsigned* sU) {
;     ...
;     bf16_t* dst = w.R2;
; #pragma unroll
;     for (int mi = 0; mi < 2; ++mi)
; #pragma unroll
;       for (int ni = 0; ni < 2; ++ni)
; #pragma unroll
;         for (int i = 0; i < 16; ++i) {
;           int row = m0 + wm * 64 + mi * 32 + crow(i, h), col = n0 + wn * 64 + ni * 32 + r;
;           const unsigned tv = totp[mi][ni][i >> 1];
;           dst[(size_t)row * 2048 + col] = (bf16_t)((i & 1) ? (tv >> 16) : (tv & 0xffffu));
;         }
;   }
	global_store_short_d16_hi v[34:35], v173, off
	global_store_short v[4:5], v176, off offset:64
	global_store_short_d16_hi v[6:7], v176, off offset:64
	global_store_short v[8:9], v170, off offset:64
	global_store_short_d16_hi v[10:11], v170, off offset:64
	global_store_short v[12:13], v175, off offset:64
	global_store_short_d16_hi v[14:15], v175, off offset:64
	global_store_short v[16:17], v174, off offset:64
	global_store_short_d16_hi v[18:19], v174, off offset:64
	global_store_short v[20:21], v172, off offset:64
	global_store_short_d16_hi v[22:23], v172, off offset:64
	global_store_short v[24:25], v171, off offset:64
	global_store_short_d16_hi v[26:27], v171, off offset:64
	global_store_short v[28:29], v169, off offset:64
	global_store_short_d16_hi v[30:31], v169, off offset:64
	global_store_short v[32:33], v168, off offset:64
	global_store_short_d16_hi v[34:35], v168, off offset:64
	v_or_b32_e32 v4, 32, v0
	v_or_b32_e32 v6, 33, v0
	v_or_b32_e32 v8, 34, v0
	v_or_b32_e32 v10, 35, v0
	v_or_b32_e32 v12, 40, v0
	v_or_b32_e32 v14, 41, v0
	v_or_b32_e32 v16, 42, v0
	v_or_b32_e32 v18, 43, v0
	v_or_b32_e32 v20, 48, v0
	v_or_b32_e32 v22, 49, v0
	v_or_b32_e32 v24, 50, v0
	v_or_b32_e32 v26, 51, v0
	v_or_b32_e32 v28, 56, v0
	v_or_b32_e32 v30, 57, v0
	v_or_b32_e32 v32, 58, v0
	v_or_b32_e32 v0, 59, v0
	v_ashrrev_i32_e32 v5, 31, v4
	v_ashrrev_i32_e32 v7, 31, v6
	v_ashrrev_i32_e32 v9, 31, v8
	v_ashrrev_i32_e32 v11, 31, v10
	v_ashrrev_i32_e32 v13, 31, v12
	v_ashrrev_i32_e32 v15, 31, v14
	v_ashrrev_i32_e32 v17, 31, v16
	v_ashrrev_i32_e32 v19, 31, v18
	v_ashrrev_i32_e32 v21, 31, v20
	v_ashrrev_i32_e32 v23, 31, v22
	v_ashrrev_i32_e32 v25, 31, v24
	v_ashrrev_i32_e32 v27, 31, v26
	v_ashrrev_i32_e32 v29, 31, v28
	v_ashrrev_i32_e32 v31, 31, v30
	v_ashrrev_i32_e32 v33, 31, v32
	v_ashrrev_i32_e32 v1, 31, v0
	v_lshlrev_b64 v[4:5], 12, v[4:5]
	v_lshlrev_b64 v[6:7], 12, v[6:7]
	v_lshlrev_b64 v[8:9], 12, v[8:9]
	v_lshlrev_b64 v[10:11], 12, v[10:11]
	v_lshlrev_b64 v[12:13], 12, v[12:13]
	v_lshlrev_b64 v[14:15], 12, v[14:15]
	v_lshlrev_b64 v[16:17], 12, v[16:17]
	v_lshlrev_b64 v[18:19], 12, v[18:19]
	v_lshlrev_b64 v[20:21], 12, v[20:21]
	v_lshlrev_b64 v[22:23], 12, v[22:23]
	v_lshlrev_b64 v[24:25], 12, v[24:25]
	v_lshlrev_b64 v[26:27], 12, v[26:27]
	v_lshlrev_b64 v[28:29], 12, v[28:29]
	v_lshlrev_b64 v[30:31], 12, v[30:31]
	v_lshlrev_b64 v[32:33], 12, v[32:33]
	v_lshlrev_b64 v[0:1], 12, v[0:1]
	v_lshl_add_u64 v[4:5], v[2:3], 0, v[4:5]
	v_lshl_add_u64 v[6:7], v[2:3], 0, v[6:7]
	v_lshl_add_u64 v[8:9], v[2:3], 0, v[8:9]
	v_lshl_add_u64 v[10:11], v[2:3], 0, v[10:11]
	v_lshl_add_u64 v[12:13], v[2:3], 0, v[12:13]
	v_lshl_add_u64 v[14:15], v[2:3], 0, v[14:15]
	v_lshl_add_u64 v[16:17], v[2:3], 0, v[16:17]
	v_lshl_add_u64 v[18:19], v[2:3], 0, v[18:19]
	v_lshl_add_u64 v[20:21], v[2:3], 0, v[20:21]
	v_lshl_add_u64 v[22:23], v[2:3], 0, v[22:23]
	v_lshl_add_u64 v[24:25], v[2:3], 0, v[24:25]
	v_lshl_add_u64 v[26:27], v[2:3], 0, v[26:27]
	v_lshl_add_u64 v[28:29], v[2:3], 0, v[28:29]
	v_lshl_add_u64 v[30:31], v[2:3], 0, v[30:31]
	v_lshl_add_u64 v[32:33], v[2:3], 0, v[32:33]
	v_lshl_add_u64 v[0:1], v[2:3], 0, v[0:1]
	global_store_short v[4:5], v167, off
	global_store_short_d16_hi v[6:7], v167, off
	global_store_short v[8:9], v164, off
	global_store_short_d16_hi v[10:11], v164, off
	global_store_short v[12:13], v163, off
	global_store_short_d16_hi v[14:15], v163, off
	global_store_short v[16:17], v161, off
	global_store_short_d16_hi v[18:19], v161, off
	global_store_short v[20:21], v155, off
	global_store_short_d16_hi v[22:23], v155, off
	global_store_short v[24:25], v154, off
	global_store_short_d16_hi v[26:27], v154, off
	global_store_short v[28:29], v153, off
	global_store_short_d16_hi v[30:31], v153, off
	global_store_short v[32:33], v152, off
	global_store_short_d16_hi v[0:1], v152, off
	global_store_short v[4:5], v151, off offset:64
	global_store_short_d16_hi v[6:7], v151, off offset:64
	global_store_short v[8:9], v150, off offset:64
	global_store_short_d16_hi v[10:11], v150, off offset:64
	global_store_short v[12:13], v149, off offset:64
	global_store_short_d16_hi v[14:15], v149, off offset:64
	global_store_short v[16:17], v148, off offset:64
	global_store_short_d16_hi v[18:19], v148, off offset:64
	global_store_short v[20:21], v147, off offset:64
	global_store_short_d16_hi v[22:23], v147, off offset:64
	global_store_short v[24:25], v146, off offset:64
	global_store_short_d16_hi v[26:27], v146, off offset:64
	global_store_short v[28:29], v145, off offset:64
	global_store_short_d16_hi v[30:31], v145, off offset:64
	global_store_short v[32:33], v144, off offset:64
	global_store_short_d16_hi v[0:1], v144, off offset:64
	s_add_i32 s69, s69, 1
	s_cmp_lg_u32 s69, s60
	s_mov_b32 s42, s71
	s_cbranch_scc1 .LBB0_861

; DI void gemm_128_deep(const bf16_t* __restrict__ A, int lda, const bf16_t* __restrict__ B, int ldb, int K, f32x16 (&acc)[2][2], bf16_t* sA, bf16_t* sBunused) {
;     ...
;   for (int k0 = 0; k0 < K - 256; k0 += 128) {
;     MMA_TILE(0)
;     ST_LDS(1, qa0, qa1, qa2, qa3, qb0, qb1, qb2, qb3)
;     GL_Q(k0 + 192)
;     __syncthreads();
;     MMA_TILE(1)
;     ST_LDS(0, pa0, pa1, pa2, pa3, pb0, pb1, pb2, pb3)
;     GL_P(k0 + 256)
;     __syncthreads();
;   }
.LBB0_954:
	ds_read_b128 v[152:155], v128
	ds_read_b128 v[168:171], v129 offset:18432
	ds_read_b128 v[172:175], v129 offset:23040
	s_mov_b32 s4, 0x1ba64000
	s_mov_b32 s38, 0x1a064000
	s_mov_b32 s6, 0x1baa4000
	s_waitcnt lgkmcnt(1)
	v_mfma_f32_32x32x16_bf16 v[48:63], v[152:155], v[168:171], v[48:63]
	s_mov_b32 s10, 0x1bac4000
	s_mov_b32 s40, 0x1a084000
	s_mov_b32 s42, 0x1a0a4000
	s_mov_b32 s44, 0x1a0c4000
	s_addk_i32 s47, 0x80
	s_cmpk_lt_u32 s47, 0x680
	s_waitcnt lgkmcnt(0)
	v_mfma_f32_32x32x16_bf16 v[32:47], v[152:155], v[172:175], v[32:47]
	ds_read_b128 v[152:155], v128 offset:4608
	s_waitcnt lgkmcnt(0)
	v_mfma_f32_32x32x16_bf16 v[16:31], v[152:155], v[168:171], v[16:31]
	v_mfma_f32_32x32x16_bf16 v[0:15], v[152:155], v[172:175], v[0:15]
	ds_read_b128 v[152:155], v128 offset:32
	ds_read_b128 v[168:171], v129 offset:18464
	ds_read_b128 v[172:175], v129 offset:23072
	s_waitcnt lgkmcnt(1)
	v_mfma_f32_32x32x16_bf16 v[48:63], v[152:155], v[168:171], v[48:63]
	s_waitcnt lgkmcnt(0)
	v_mfma_f32_32x32x16_bf16 v[32:47], v[152:155], v[172:175], v[32:47]
	ds_read_b128 v[152:155], v128 offset:4640
	s_waitcnt lgkmcnt(0)
	v_mfma_f32_32x32x16_bf16 v[16:31], v[152:155], v[168:171], v[16:31]
	ds_read_b128 v[168:171], v128 offset:64
	v_mfma_f32_32x32x16_bf16 v[0:15], v[152:155], v[172:175], v[0:15]
	ds_read_b128 v[176:179], v128 offset:4672
	ds_read_b128 v[172:175], v129 offset:18496
	ds_read_b128 v[194:197], v129 offset:23104
	ds_read_b128 v[198:201], v128 offset:96
	ds_read_b128 v[202:205], v128 offset:4704
	ds_read_b128 v[206:209], v129 offset:18528
	ds_read_b128 v[210:213], v129 offset:23136
	s_setprio 1
	s_waitcnt vmcnt(15)
	ds_write_b128 v130, v[108:111] offset:36864
	s_waitcnt vmcnt(14)
	ds_write_b128 v130, v[96:99] offset:41472
	s_waitcnt vmcnt(13)
	ds_write_b128 v130, v[100:103] offset:46080
	s_waitcnt vmcnt(12)
	ds_write_b128 v130, v[104:107] offset:50688
	s_waitcnt vmcnt(11)
	ds_write_b128 v130, v[112:115] offset:55296
	s_waitcnt vmcnt(10)
	ds_write_b128 v130, v[116:119] offset:59904
	s_waitcnt vmcnt(9)
	ds_write_b128 v130, v[120:123] offset:64512
	v_lshl_add_u64 v[96:97], v[150:151], 0, v[156:157]
	v_lshl_add_u64 v[98:99], v[148:149], 0, v[156:157]
	v_add_co_u32_e32 v152, vcc, s4, v96
	s_mov_b32 s4, 0x1ba84000
	s_waitcnt lgkmcnt(12)
	v_mfma_f32_32x32x16_bf16 v[48:63], v[168:171], v[172:175], v[48:63]
	s_waitcnt vmcnt(8)
	ds_write_b128 v131, v[124:127] offset:13824
	v_add_co_u32_e64 v154, s[4:5], s4, v96
	v_addc_co_u32_e32 v153, vcc, 0, v97, vcc
	s_nop 0
	v_addc_co_u32_e64 v155, vcc, 0, v97, s[4:5]
	s_waitcnt lgkmcnt(12)
	v_mfma_f32_32x32x16_bf16 v[32:47], v[168:171], v[194:197], v[32:47]
	v_add_co_u32_e64 v168, s[6:7], s6, v96
	v_add_co_u32_e64 v170, s[10:11], s10, v96
	s_nop 0
	v_addc_co_u32_e64 v169, vcc, 0, v97, s[6:7]
	v_addc_co_u32_e64 v171, vcc, 0, v97, s[10:11]
	v_mfma_f32_32x32x16_bf16 v[16:31], v[176:179], v[172:175], v[16:31]
	v_add_co_u32_e64 v172, s[38:39], s38, v98
	v_add_co_u32_e64 v174, s[40:41], s40, v98
	s_nop 0
	v_addc_co_u32_e64 v173, vcc, 0, v99, s[38:39]
	v_addc_co_u32_e64 v175, vcc, 0, v99, s[40:41]
	v_mfma_f32_32x32x16_bf16 v[0:15], v[176:179], v[194:197], v[0:15]
	v_add_co_u32_e64 v176, s[42:43], s42, v98
	v_add_co_u32_e64 v178, s[44:45], s44, v98
	s_nop 0
	v_addc_co_u32_e64 v177, vcc, 0, v99, s[42:43]
	v_addc_co_u32_e64 v179, vcc, 0, v99, s[44:45]
	s_waitcnt lgkmcnt(9)
	v_mfma_f32_32x32x16_bf16 v[48:63], v[198:201], v[206:209], v[48:63]
	global_load_dwordx4 v[108:111], v[152:153], off offset:2176
	global_load_dwordx4 v[96:99], v[154:155], off offset:2176
	global_load_dwordx4 v[100:103], v[168:169], off offset:2176
	global_load_dwordx4 v[104:107], v[170:171], off offset:2176
	global_load_dwordx4 v[112:115], v[172:173], off offset:2176
	global_load_dwordx4 v[116:119], v[174:175], off offset:2176
	global_load_dwordx4 v[120:123], v[176:177], off offset:2176
	global_load_dwordx4 v[124:127], v[178:179], off offset:2176
	s_waitcnt lgkmcnt(0)
	s_barrier
	s_setprio 2
	v_lshl_add_u64 v[148:149], v[148:149], 0, s[94:95]
	v_lshl_add_u64 v[150:151], v[150:151], 0, s[94:95]
	v_mfma_f32_32x32x16_bf16 v[32:47], v[198:201], v[210:213], v[32:47]
	ds_read_b128 v[194:197], v128 offset:36864
	ds_read_b128 v[198:201], v129 offset:55296
	v_mfma_f32_32x32x16_bf16 v[16:31], v[202:205], v[206:209], v[16:31]
	v_mfma_f32_32x32x16_bf16 v[0:15], v[202:205], v[210:213], v[0:15]
	ds_read_b128 v[202:205], v129 offset:59904
	s_waitcnt lgkmcnt(1)
	v_mfma_f32_32x32x16_bf16 v[48:63], v[194:197], v[198:201], v[48:63]
	s_waitcnt lgkmcnt(0)
	v_mfma_f32_32x32x16_bf16 v[32:47], v[194:197], v[202:205], v[32:47]
	ds_read_b128 v[194:197], v128 offset:41472
	s_waitcnt lgkmcnt(0)
	v_mfma_f32_32x32x16_bf16 v[16:31], v[194:197], v[198:201], v[16:31]
	v_mfma_f32_32x32x16_bf16 v[0:15], v[194:197], v[202:205], v[0:15]
	ds_read_b128 v[194:197], v128 offset:36896
	ds_read_b128 v[198:201], v129 offset:55328
	ds_read_b128 v[202:205], v129 offset:59936
	s_waitcnt lgkmcnt(1)
	v_mfma_f32_32x32x16_bf16 v[48:63], v[194:197], v[198:201], v[48:63]
	s_waitcnt lgkmcnt(0)
	v_mfma_f32_32x32x16_bf16 v[32:47], v[194:197], v[202:205], v[32:47]
	ds_read_b128 v[194:197], v128 offset:41504
	s_waitcnt lgkmcnt(0)
	v_mfma_f32_32x32x16_bf16 v[16:31], v[194:197], v[198:201], v[16:31]
	v_mfma_f32_32x32x16_bf16 v[0:15], v[194:197], v[202:205], v[0:15]
	ds_read_b128 v[194:197], v128 offset:36928
	ds_read_b128 v[198:201], v129 offset:55360
	ds_read_b128 v[202:205], v129 offset:59968
	s_waitcnt lgkmcnt(1)
	v_mfma_f32_32x32x16_bf16 v[48:63], v[194:197], v[198:201], v[48:63]
	s_waitcnt lgkmcnt(0)
	v_mfma_f32_32x32x16_bf16 v[32:47], v[194:197], v[202:205], v[32:47]
	ds_read_b128 v[194:197], v128 offset:41536
	s_waitcnt lgkmcnt(0)
	v_mfma_f32_32x32x16_bf16 v[16:31], v[194:197], v[198:201], v[16:31]
	v_mfma_f32_32x32x16_bf16 v[0:15], v[194:197], v[202:205], v[0:15]
	ds_read_b128 v[194:197], v128 offset:36960
	ds_read_b128 v[198:201], v129 offset:55392
	ds_read_b128 v[202:205], v128 offset:41568
	ds_read_b128 v[206:209], v129 offset:60000
	s_setprio 1
	s_waitcnt vmcnt(13)
	ds_write_b128 v130, v[92:95]
	ds_write_b128 v130, v[64:67] offset:4608
	ds_write_b128 v130, v[68:71] offset:9216
	s_waitcnt vmcnt(11)
	ds_write_b128 v130, v[84:87] offset:13824
	ds_write_b128 v130, v[72:75] offset:18432
	s_waitcnt vmcnt(10)
	ds_write_b128 v130, v[76:79] offset:23040
	s_waitcnt vmcnt(9)
	ds_write_b128 v130, v[80:83] offset:27648
	s_waitcnt vmcnt(8)
	ds_write_b128 v130, v[88:91] offset:32256
	global_load_dwordx4 v[92:95], v[152:153], off offset:2304
	global_load_dwordx4 v[64:67], v[154:155], off offset:2304
	global_load_dwordx4 v[68:71], v[168:169], off offset:2304
	global_load_dwordx4 v[84:87], v[170:171], off offset:2304
	global_load_dwordx4 v[72:75], v[172:173], off offset:2304
	global_load_dwordx4 v[76:79], v[174:175], off offset:2304
	global_load_dwordx4 v[80:83], v[176:177], off offset:2304
	global_load_dwordx4 v[88:91], v[178:179], off offset:2304
	s_waitcnt lgkmcnt(0)
	s_barrier
; DI void gemm_128_deep(const bf16_t* __restrict__ A, int lda, const bf16_t* __restrict__ B, int ldb, int K, f32x16 (&acc)[2][2], bf16_t* sA, bf16_t* sBunused) {
;     ...
;   for (int k0 = 0; k0 < K - 256; k0 += 128) {
;     MMA_TILE(0)
;     ST_LDS(1, qa0, qa1, qa2, qa3, qb0, qb1, qb2, qb3)
;     GL_Q(k0 + 192)
;     __syncthreads();
;     MMA_TILE(1)
;     ST_LDS(0, pa0, pa1, pa2, pa3, pb0, pb1, pb2, pb3)
;     GL_P(k0 + 256)
;     __syncthreads();
;   }
;   MMA_TILE(0)
;   ST_LDS(1, qa0, qa1, qa2, qa3, qb0, qb1, qb2, qb3)
;   GL_Q(K - 64)
;   __syncthreads();
;   MMA_TILE(1)
;   ST_LDS(0, pa0, pa1, pa2, pa3, pb0, pb1, pb2, pb3)
;   __syncthreads();
; DI void phase_out(CP p, const Ptrs& w, int l, bf16_t* sA, bf16_t* sB) {
;     ...
;     int b = m0 / TPB, ib = m0 - b * TPB;
;     bool isctx = ib < CTXL;
;     f32x16 acc[2][2];
;     zero_acc(acc);
;     gemm_128_deep(w.R2 + (size_t)m0 * 2048, 2048, out_t + (size_t)n0 * 2048, 2048, 2048, acc, sA, sB);
;     const float* gate = w.mod + (l * 3 + (isctx ? 2 : b)) * 6144 + 4096;
	s_setprio 2
	v_mfma_f32_32x32x16_bf16 v[48:63], v[194:197], v[198:201], v[48:63]
	v_mfma_f32_32x32x16_bf16 v[32:47], v[194:197], v[206:209], v[32:47]
	v_mfma_f32_32x32x16_bf16 v[16:31], v[202:205], v[198:201], v[16:31]
	v_mfma_f32_32x32x16_bf16 v[0:15], v[202:205], v[206:209], v[0:15]
	s_cbranch_scc1 .LBB0_954
	ds_read_b128 v[148:151], v128
	ds_read_b128 v[152:155], v129 offset:18432
	ds_read_b128 v[168:171], v129 offset:23040
	s_mul_hi_i32 s4, s90, 0x3e0f83e1
	s_lshr_b32 s5, s4, 31
	s_ashr_i32 s39, s4, 4
	s_waitcnt lgkmcnt(1)
	v_mfma_f32_32x32x16_bf16 v[48:63], v[148:151], v[152:155], v[48:63]
	s_add_i32 s39, s39, s5
	s_mul_i32 s38, s39, 0x2100
	s_sub_i32 s10, s48, s38
	s_cmpk_lt_i32 s10, 0x100
	s_cselect_b64 s[4:5], -1, 0
	s_and_b64 s[6:7], s[4:5], exec
	s_cselect_b32 s6, 2, s39
	s_waitcnt lgkmcnt(0)
	v_mfma_f32_32x32x16_bf16 v[32:47], v[148:151], v[168:171], v[32:47]
	ds_read_b128 v[148:151], v128 offset:4608
	v_readlane_b32 s7, v254, 56
	s_add_i32 s6, s6, s7
	s_mulk_i32 s6, 0x1800
	s_ashr_i32 s7, s6, 31
	s_lshl_b64 s[6:7], s[6:7], 2
	s_add_u32 s6, s78, s6
	s_waitcnt lgkmcnt(0)
	v_mfma_f32_32x32x16_bf16 v[16:31], v[148:151], v[152:155], v[16:31]
	s_addc_u32 s7, s79, s7
	s_add_u32 s6, s6, 0x4000
	s_addc_u32 s7, s7, 0
	v_readlane_b32 s40, v254, 54
	v_readlane_b32 s41, v254, 55
	s_and_b64 vcc, exec, s[40:41]
	v_mfma_f32_32x32x16_bf16 v[0:15], v[148:151], v[168:171], v[0:15]
	ds_read_b128 v[148:151], v128 offset:32
	ds_read_b128 v[152:155], v129 offset:18464
	ds_read_b128 v[168:171], v129 offset:23072
	s_waitcnt lgkmcnt(1)
	v_mfma_f32_32x32x16_bf16 v[48:63], v[148:151], v[152:155], v[48:63]
	s_waitcnt lgkmcnt(0)
	v_mfma_f32_32x32x16_bf16 v[32:47], v[148:151], v[168:171], v[32:47]
	ds_read_b128 v[148:151], v128 offset:4640
	s_waitcnt lgkmcnt(0)
	v_mfma_f32_32x32x16_bf16 v[16:31], v[148:151], v[152:155], v[16:31]
	v_mfma_f32_32x32x16_bf16 v[0:15], v[148:151], v[168:171], v[0:15]
	ds_read_b128 v[148:151], v128 offset:64
	ds_read_b128 v[152:155], v129 offset:18496
	ds_read_b128 v[168:171], v129 offset:23104
	s_waitcnt lgkmcnt(1)
	v_mfma_f32_32x32x16_bf16 v[48:63], v[148:151], v[152:155], v[48:63]
	s_waitcnt lgkmcnt(0)
	v_mfma_f32_32x32x16_bf16 v[32:47], v[148:151], v[168:171], v[32:47]
	ds_read_b128 v[148:151], v128 offset:4672
	s_waitcnt lgkmcnt(0)
	v_mfma_f32_32x32x16_bf16 v[16:31], v[148:151], v[152:155], v[16:31]
	v_mfma_f32_32x32x16_bf16 v[0:15], v[148:151], v[168:171], v[0:15]
	ds_read_b128 v[148:151], v128 offset:96
	ds_read_b128 v[152:155], v129 offset:18528
	ds_read_b128 v[168:171], v129 offset:23136
	s_waitcnt lgkmcnt(1)
	v_mfma_f32_32x32x16_bf16 v[48:63], v[148:151], v[152:155], v[48:63]
	s_waitcnt lgkmcnt(0)
	v_mfma_f32_32x32x16_bf16 v[32:47], v[148:151], v[168:171], v[32:47]
	ds_read_b128 v[148:151], v128 offset:4704
	s_setprio 1
	s_waitcnt vmcnt(15)
	ds_write_b128 v130, v[108:111] offset:36864
	s_waitcnt vmcnt(14)
	ds_write_b128 v130, v[96:99] offset:41472
	s_waitcnt vmcnt(13)
	ds_write_b128 v130, v[100:103] offset:46080
	s_waitcnt vmcnt(12)
	ds_write_b128 v130, v[104:107] offset:50688
	s_waitcnt vmcnt(11)
	ds_write_b128 v130, v[112:115] offset:55296
	s_waitcnt vmcnt(10)
	ds_write_b128 v130, v[116:119] offset:59904
	s_waitcnt vmcnt(9)
	ds_write_b128 v130, v[120:123] offset:64512
	s_waitcnt vmcnt(8)
	ds_write_b128 v131, v[124:127] offset:13824
	global_load_dwordx4 v[96:99], v[142:143], off offset:3968
	global_load_dwordx4 v[100:103], v[138:139], off offset:3968
	global_load_dwordx4 v[104:107], v[144:145], off offset:3968
	global_load_dwordx4 v[108:111], v[146:147], off offset:3968
	global_load_dwordx4 v[112:115], v[132:133], off offset:3968
	global_load_dwordx4 v[116:119], v[134:135], off offset:3968
	global_load_dwordx4 v[120:123], v[136:137], off offset:3968
	global_load_dwordx4 v[124:127], v[140:141], off offset:3968
	s_waitcnt lgkmcnt(0)
	s_barrier
	s_setprio 2
	ds_read_b128 v[132:135], v128 offset:36864
	ds_read_b128 v[136:139], v129 offset:55296
	ds_read_b128 v[140:143], v129 offset:59904
	s_waitcnt lgkmcnt(1)
	v_mfma_f32_32x32x16_bf16 v[48:63], v[132:135], v[136:139], v[48:63]
	s_waitcnt lgkmcnt(0)
	v_mfma_f32_32x32x16_bf16 v[32:47], v[132:135], v[140:143], v[32:47]
	ds_read_b128 v[132:135], v128 offset:41472
	v_mfma_f32_32x32x16_bf16 v[16:31], v[148:151], v[152:155], v[16:31]
	v_mfma_f32_32x32x16_bf16 v[0:15], v[148:151], v[168:171], v[0:15]
	s_waitcnt lgkmcnt(0)
	v_mfma_f32_32x32x16_bf16 v[16:31], v[132:135], v[136:139], v[16:31]
	v_mfma_f32_32x32x16_bf16 v[0:15], v[132:135], v[140:143], v[0:15]
	ds_read_b128 v[132:135], v128 offset:36896
	ds_read_b128 v[136:139], v129 offset:55328
	ds_read_b128 v[140:143], v129 offset:59936
	s_waitcnt lgkmcnt(1)
	v_mfma_f32_32x32x16_bf16 v[48:63], v[132:135], v[136:139], v[48:63]
	s_waitcnt lgkmcnt(0)
	v_mfma_f32_32x32x16_bf16 v[32:47], v[132:135], v[140:143], v[32:47]
	ds_read_b128 v[132:135], v128 offset:41504
	s_waitcnt lgkmcnt(0)
	v_mfma_f32_32x32x16_bf16 v[16:31], v[132:135], v[136:139], v[16:31]
	v_mfma_f32_32x32x16_bf16 v[0:15], v[132:135], v[140:143], v[0:15]
	ds_read_b128 v[132:135], v128 offset:36928
	ds_read_b128 v[136:139], v129 offset:55360
	ds_read_b128 v[140:143], v129 offset:59968
	s_waitcnt lgkmcnt(1)
	v_mfma_f32_32x32x16_bf16 v[48:63], v[132:135], v[136:139], v[48:63]
	s_waitcnt lgkmcnt(0)
	v_mfma_f32_32x32x16_bf16 v[32:47], v[132:135], v[140:143], v[32:47]
	ds_read_b128 v[132:135], v128 offset:41536
	s_waitcnt lgkmcnt(0)
	v_mfma_f32_32x32x16_bf16 v[16:31], v[132:135], v[136:139], v[16:31]
	v_mfma_f32_32x32x16_bf16 v[0:15], v[132:135], v[140:143], v[0:15]
	ds_read_b128 v[132:135], v128 offset:36960
	ds_read_b128 v[136:139], v129 offset:55392
	ds_read_b128 v[140:143], v129 offset:60000
	s_waitcnt lgkmcnt(1)
	v_mfma_f32_32x32x16_bf16 v[48:63], v[132:135], v[136:139], v[48:63]
	s_waitcnt lgkmcnt(0)
	v_mfma_f32_32x32x16_bf16 v[32:47], v[132:135], v[140:143], v[32:47]
	ds_read_b128 v[132:135], v128 offset:41568
	s_setprio 1
	s_waitcnt vmcnt(15)
	ds_write_b128 v130, v[92:95]
	s_waitcnt vmcnt(14)
	ds_write_b128 v130, v[64:67] offset:4608
	s_waitcnt vmcnt(13)
	ds_write_b128 v130, v[68:71] offset:9216
	s_waitcnt vmcnt(12)
	ds_write_b128 v130, v[84:87] offset:13824
	s_waitcnt vmcnt(11)
	ds_write_b128 v130, v[72:75] offset:18432
	s_waitcnt vmcnt(10)
	ds_write_b128 v130, v[76:79] offset:23040
	s_waitcnt vmcnt(9)
	ds_write_b128 v130, v[80:83] offset:27648
	s_waitcnt vmcnt(8)
	ds_write_b128 v130, v[88:91] offset:32256
	s_waitcnt lgkmcnt(0)
	s_barrier
; DI int crow(int i, int h) { return (i & 3) + 8 * (i >> 2) + 4 * h; }
; DI void gemm_128_deep(const bf16_t* __restrict__ A, int lda, const bf16_t* __restrict__ B, int ldb, int K, f32x16 (&acc)[2][2], bf16_t* sA, bf16_t* sBunused) {
;     ...
;   MMA_TILE(1)
;   ST_LDS(0, pa0, pa1, pa2, pa3, pb0, pb1, pb2, pb3)
;   __syncthreads();
;   MMA_TILE(0)
;   ST_LDS(1, qa0, qa1, qa2, qa3, qb0, qb1, qb2, qb3)
;   __syncthreads();
;   MMA_TILE(1)
;   __syncthreads();
; DI void phase_out(CP p, const Ptrs& w, int l, bf16_t* sA, bf16_t* sB) {
;     ...
;     int b = m0 / TPB, ib = m0 - b * TPB;
;     bool isctx = ib < CTXL;
;     f32x16 acc[2][2];
;     zero_acc(acc);
;     gemm_128_deep(w.R2 + (size_t)m0 * 2048, 2048, out_t + (size_t)n0 * 2048, 2048, 2048, acc, sA, sB);
;     const float* gate = w.mod + (l * 3 + (isctx ? 2 : b)) * 6144 + 4096;
; #pragma unroll
;     for (int mi = 0; mi < 2; ++mi)
; #pragma unroll
;       for (int ni = 0; ni < 2; ++ni) {
;         int col = n0 + wn * 64 + ni * 32 + r;
;         float gt = gate[col];
; #pragma unroll
;         for (int i = 0; i < 16; ++i) {
;           int ii = ib + wm * 64 + mi * 32 + crow(i, h);
;           const float* src = xrow(p, w, l, b * TPB + ii);
;           float* dstp = isctx ? w.xc1 + (size_t)(b * CTXL + ii) * DM : p.out + (size_t)(b * 8192 + ii - CTXL) * DM;
;           dstp[col] = src[col] + gt * acc[mi][ni][i];
	s_setprio 2
	ds_read_b128 v[64:67], v128
	ds_read_b128 v[68:71], v129 offset:18432
	ds_read_b128 v[72:75], v129 offset:23040
	s_waitcnt lgkmcnt(1)
	v_mfma_f32_32x32x16_bf16 v[48:63], v[64:67], v[68:71], v[48:63]
	v_add_u32_e32 v92, s10, v163
	s_mov_b64 s[10:11], -1
	s_waitcnt lgkmcnt(0)
	v_mfma_f32_32x32x16_bf16 v[32:47], v[64:67], v[72:75], v[32:47]
	ds_read_b128 v[64:67], v128 offset:4608
	v_mfma_f32_32x32x16_bf16 v[16:31], v[132:135], v[136:139], v[16:31]
	v_mfma_f32_32x32x16_bf16 v[0:15], v[132:135], v[140:143], v[0:15]
	s_waitcnt lgkmcnt(0)
	v_mfma_f32_32x32x16_bf16 v[16:31], v[64:67], v[68:71], v[16:31]
	v_mfma_f32_32x32x16_bf16 v[0:15], v[64:67], v[72:75], v[0:15]
	ds_read_b128 v[64:67], v128 offset:32
	ds_read_b128 v[68:71], v129 offset:18464
	ds_read_b128 v[72:75], v129 offset:23072
	s_waitcnt lgkmcnt(1)
	v_mfma_f32_32x32x16_bf16 v[48:63], v[64:67], v[68:71], v[48:63]
	s_waitcnt lgkmcnt(0)
	v_mfma_f32_32x32x16_bf16 v[32:47], v[64:67], v[72:75], v[32:47]
	ds_read_b128 v[64:67], v128 offset:4640
	s_waitcnt lgkmcnt(0)
	v_mfma_f32_32x32x16_bf16 v[16:31], v[64:67], v[68:71], v[16:31]
	v_mfma_f32_32x32x16_bf16 v[0:15], v[64:67], v[72:75], v[0:15]
	ds_read_b128 v[64:67], v128 offset:64
	ds_read_b128 v[68:71], v129 offset:18496
	ds_read_b128 v[72:75], v129 offset:23104
	s_waitcnt lgkmcnt(1)
	v_mfma_f32_32x32x16_bf16 v[48:63], v[64:67], v[68:71], v[48:63]
	s_waitcnt lgkmcnt(0)
	v_mfma_f32_32x32x16_bf16 v[32:47], v[64:67], v[72:75], v[32:47]
	ds_read_b128 v[64:67], v128 offset:4672
	s_waitcnt lgkmcnt(0)
	v_mfma_f32_32x32x16_bf16 v[16:31], v[64:67], v[68:71], v[16:31]
	v_mfma_f32_32x32x16_bf16 v[0:15], v[64:67], v[72:75], v[0:15]
	ds_read_b128 v[64:67], v128 offset:96
	ds_read_b128 v[68:71], v129 offset:18528
	ds_read_b128 v[72:75], v129 offset:23136
	s_waitcnt lgkmcnt(1)
	v_mfma_f32_32x32x16_bf16 v[48:63], v[64:67], v[68:71], v[48:63]
	s_waitcnt lgkmcnt(0)
	v_mfma_f32_32x32x16_bf16 v[32:47], v[64:67], v[72:75], v[32:47]
	ds_read_b128 v[64:67], v128 offset:4704
	s_setprio 1
	s_waitcnt vmcnt(7)
	ds_write_b128 v130, v[96:99] offset:36864
	s_waitcnt vmcnt(6)
	ds_write_b128 v130, v[100:103] offset:41472
	s_waitcnt vmcnt(5)
	ds_write_b128 v130, v[104:107] offset:46080
	s_waitcnt vmcnt(4)
	ds_write_b128 v130, v[108:111] offset:50688
	s_waitcnt vmcnt(3)
	ds_write_b128 v130, v[112:115] offset:55296
	s_waitcnt vmcnt(2)
	ds_write_b128 v130, v[116:119] offset:59904
	s_waitcnt vmcnt(1)
	ds_write_b128 v130, v[120:123] offset:64512
	s_waitcnt vmcnt(0)
	ds_write_b128 v131, v[124:127] offset:13824
	s_waitcnt lgkmcnt(0)
	s_barrier
	s_setprio 2
	v_mfma_f32_32x32x16_bf16 v[16:31], v[64:67], v[68:71], v[16:31]
	v_mfma_f32_32x32x16_bf16 v[0:15], v[64:67], v[72:75], v[0:15]
	ds_read_b128 v[64:67], v128 offset:36864
	ds_read_b128 v[68:71], v129 offset:55296
	ds_read_b128 v[72:75], v129 offset:59904
	s_waitcnt lgkmcnt(1)
	v_mfma_f32_32x32x16_bf16 v[48:63], v[64:67], v[68:71], v[48:63]
	s_waitcnt lgkmcnt(0)
	v_mfma_f32_32x32x16_bf16 v[32:47], v[64:67], v[72:75], v[32:47]
	ds_read_b128 v[64:67], v128 offset:41472
	s_waitcnt lgkmcnt(0)
	v_mfma_f32_32x32x16_bf16 v[16:31], v[64:67], v[68:71], v[16:31]
	v_mfma_f32_32x32x16_bf16 v[0:15], v[64:67], v[72:75], v[0:15]
	ds_read_b128 v[64:67], v128 offset:36896
	ds_read_b128 v[68:71], v129 offset:55328
	ds_read_b128 v[72:75], v129 offset:59936
	s_waitcnt lgkmcnt(1)
	v_mfma_f32_32x32x16_bf16 v[48:63], v[64:67], v[68:71], v[48:63]
	s_waitcnt lgkmcnt(0)
	v_mfma_f32_32x32x16_bf16 v[32:47], v[64:67], v[72:75], v[32:47]
	ds_read_b128 v[64:67], v128 offset:41504
	s_waitcnt lgkmcnt(0)
	v_mfma_f32_32x32x16_bf16 v[16:31], v[64:67], v[68:71], v[16:31]
	v_mfma_f32_32x32x16_bf16 v[0:15], v[64:67], v[72:75], v[0:15]
	ds_read_b128 v[64:67], v128 offset:36928
	ds_read_b128 v[68:71], v129 offset:55360
	ds_read_b128 v[72:75], v129 offset:59968
	s_waitcnt lgkmcnt(1)
	v_mfma_f32_32x32x16_bf16 v[48:63], v[64:67], v[68:71], v[48:63]
	s_waitcnt lgkmcnt(0)
	v_mfma_f32_32x32x16_bf16 v[32:47], v[64:67], v[72:75], v[32:47]
	ds_read_b128 v[64:67], v128 offset:41536
	s_waitcnt lgkmcnt(0)
	v_mfma_f32_32x32x16_bf16 v[16:31], v[64:67], v[68:71], v[16:31]
	ds_read_b128 v[68:71], v128 offset:36960
	ds_read_b128 v[76:79], v128 offset:41568
	ds_read_b128 v[80:83], v129 offset:55392
	ds_read_b128 v[84:87], v129 offset:60000
	s_waitcnt lgkmcnt(0)
	s_barrier
	s_setprio 2
	v_mfma_f32_32x32x16_bf16 v[0:15], v[64:67], v[72:75], v[0:15]
	v_or_b32_e32 v64, s46, v161
	v_ashrrev_i32_e32 v65, 31, v64
	v_or_b32_e32 v72, v92, v164
	v_add_u32_e32 v66, s38, v72
	v_mul_hi_i32 v67, v66, s0
	v_mfma_f32_32x32x16_bf16 v[48:63], v[68:71], v[80:83], v[48:63]
	v_mfma_f32_32x32x16_bf16 v[32:47], v[68:71], v[84:87], v[32:47]
	v_lshl_add_u64 v[68:69], v[64:65], 2, s[6:7]
	global_load_dword v90, v[68:69], off
	v_lshrrev_b32_e32 v70, 31, v67
	v_ashrrev_i32_e32 v67, 11, v67
	v_add_u32_e32 v93, v67, v70
	v_mad_i32_i24 v94, v93, s1, v66
	v_cmp_lt_i32_e64 s[42:43], s37, v94
	v_mfma_f32_32x32x16_bf16 v[16:31], v[76:79], v[80:83], v[16:31]
	v_mfma_f32_32x32x16_bf16 v[0:15], v[76:79], v[84:87], v[0:15]
	s_setprio 0
	s_cbranch_vccz .LBB0_961
	s_and_saveexec_b64 s[10:11], s[42:43]
	s_xor_b64 s[10:11], exec, s[10:11]
	v_lshlrev_b32_e32 v66, 13, v93
	s_movk_i32 s40, 0xff00
	v_add3_u32 v66, v66, v94, s40
	s_or_saveexec_b64 s[10:11], s[10:11]
	v_mov_b64_e32 v[70:71], s[76:77]
	s_xor_b64 exec, exec, s[10:11]
	v_lshl_add_u32 v66, v93, 8, v94
	v_mov_b64_e32 v[70:71], s[12:13]
	s_or_b64 exec, exec, s[10:11]
	s_mov_b64 s[10:11], 0
